# GEMM K loops: all fragment ds_reads of each barrier-bounded phase issued first, ahead of SALU / DMA address math / LDS-DMA issue (m0 wait states kept)
# baseline (speedup 1.0000x reference)
; #define PG8_STAGE(bufoff, gbase, voff) do { _Pragma("unroll") for (int _i = 0; _i < 2; ++_i) \
;         __builtin_amdgcn_global_load_lds((const unsigned*)((const char*)(gbase) + (voff)[_i]), (PG8_LAS unsigned*)(lds + (bufoff) + ldsw + _i * 8192), 16, 0, 0); } while (0)
; #define PG8_LDA(dst, b, h) do { _Pragma("unroll") for (int m = 0; m < 4; ++m) _Pragma("unroll") for (int k = 0; k < 2; ++k) dst[m][k] = *(const PG8_LAS bf16x8*)(lds + PG8_SA(b, h) + aoff + m * 2048 + k * 1024); } while (0)
; #define PG8_LDB(dst, b, h) do { _Pragma("unroll") for (int n = 0; n < 2; ++n) _Pragma("unroll") for (int k = 0; k < 2; ++k) dst[n][k] = *(const PG8_LAS bf16x8*)(lds + PG8_SB(b, h) + boff + n * 2048 + k * 1024); } while (0)
; #define PG8_MMA(ai, bj, At, Bt) do { __builtin_amdgcn_s_setprio(1); _Pragma("unroll") for (int m = 0; m < 4; ++m) _Pragma("unroll") for (int n = 0; n < 2; ++n) _Pragma("unroll") for (int k = 0; k < 2; ++k) \
;         acc[ai][bj][m][n] = __builtin_amdgcn_mfma_f32_16x16x32_bf16(Bt[n][k], At[m][k], acc[ai][bj][m][n], 0, 0, 0); __builtin_amdgcn_s_setprio(0); } while (0)
; #define PG8_WAIT_V(n) asm volatile("s_waitcnt vmcnt(" #n ")" ::: "memory")
; #define PG8_WAIT_L(n) asm volatile("s_waitcnt lgkmcnt(" #n ")" ::: "memory")
; #define PG8_BAR __builtin_amdgcn_s_barrier()
; #define PG8_SCHED __builtin_amdgcn_sched_barrier(0)
; template <class Epi, class Sched, bool ALIGN_EPI = false, bool SP2 = false>
; __device__ __forceinline__ void gemm_phase(PG8_LAS unsigned char* lds, const Gemm g, const Sched S, const Epi E) {
;     ...
;             const bool last = (t == nt - 2);
;             const char* a1 = cA + (size_t)(t + 1) * kstep;
;             const char* a2 = last ? nA : cA + (size_t)(t + 2) * kstep; const char* b2 = last ? nB : cB + (size_t)(t + 2) * kstep;
;             const char* a3 = a2 + kstep; const char* b3 = b2 + kstep;
;             if (last && has_next) S.a_ready(nxt);
;             if constexpr (SP2) {
;             PG8_LDB(B0, 0, 0); PG8_LDB(B1, 0, 1); PG8_SCHED; PG8_LDA(At, 0, 0); PG8_STAGE(PG8_SA(1, 1), a1 + hstep, voffA);
;             PG8_WAIT_V(8); PG8_WAIT_L(0); PG8_BAR; PG8_MMA(0, 0, At, B0); PG8_MMA(0, 1, At, B1); PG8_BAR; PG8_SCHED;
;             PG8_LDA(At, 0, 1); PG8_STAGE(PG8_SB(0, 0), b2, voffB); PG8_STAGE(PG8_SB(0, 1), b2 + hstep, voffB); PG8_STAGE(PG8_SA(0, 0), a2, voffA);
.LBB0_180:
	v_add_u32_e32 v140, 0x10000, v143
	ds_read_b128 v[154:157], v140
	ds_read_b128 v[158:161], v140 offset:1024
	ds_read_b128 v[162:165], v140 offset:2048
	ds_read_b128 v[166:169], v140 offset:3072
	v_add_u32_e32 v140, 0x14000, v143
	ds_read_b128 v[170:173], v140
	ds_read_b128 v[174:177], v140 offset:1024
	ds_read_b128 v[182:185], v140 offset:2048
	ds_read_b128 v[198:201], v140 offset:3072
	ds_read_b128 v[202:205], v146
	ds_read_b128 v[206:209], v146 offset:1024
	ds_read_b128 v[210:213], v146 offset:2048
	ds_read_b128 v[214:217], v146 offset:3072
	ds_read_b128 v[218:221], v146 offset:4096
	ds_read_b128 v[222:225], v146 offset:5120
	ds_read_b128 v[226:229], v146 offset:6144
	ds_read_b128 v[230:233], v146 offset:7168
	s_add_i32 s20, s18, 2
	s_add_u32 s21, s16, 0x80
	s_addc_u32 s19, s17, 0
	s_add_i32 s25, 0, 0x10000
	s_cmp_eq_u32 s75, s18
	s_cselect_b32 s19, s1, s19
	s_cselect_b32 s18, s0, s21
	s_cselect_b32 s23, s59, s15
	s_cselect_b32 s22, s58, s14
	s_add_i32 s21, 0, 0x14000
	v_lshl_add_u64 v[140:141], s[16:17], 0, v[136:137]
	s_add_i32 m0, s68, 0xc000
	s_nop 0
	global_load_lds_dwordx4 v[140:141], off
	v_lshl_add_u64 v[140:141], s[16:17], 0, v[138:139]
	s_add_i32 m0, s68, 0xe000
	s_nop 0
	global_load_lds_dwordx4 v[140:141], off
	s_waitcnt vmcnt(8)
	s_waitcnt lgkmcnt(0)
	s_barrier
	s_setprio 1
	s_waitcnt lgkmcnt(0)
	v_mfma_f32_16x16x32_bf16 v[126:129], v[154:157], v[202:205], v[126:129]
	v_mfma_f32_16x16x32_bf16 v[118:121], v[162:165], v[202:205], v[118:121]
	v_mfma_f32_16x16x32_bf16 v[110:113], v[154:157], v[210:213], v[110:113]
	v_mfma_f32_16x16x32_bf16 v[102:105], v[162:165], v[210:213], v[102:105]
	v_mfma_f32_16x16x32_bf16 v[94:97], v[154:157], v[218:221], v[94:97]
	v_mfma_f32_16x16x32_bf16 v[86:89], v[162:165], v[218:221], v[86:89]
	v_mfma_f32_16x16x32_bf16 v[78:81], v[154:157], v[226:229], v[78:81]
	v_mfma_f32_16x16x32_bf16 v[70:73], v[162:165], v[226:229], v[70:73]
	v_mfma_f32_16x16x32_bf16 v[126:129], v[158:161], v[206:209], v[126:129]
	v_mfma_f32_16x16x32_bf16 v[118:121], v[166:169], v[206:209], v[118:121]
	v_mfma_f32_16x16x32_bf16 v[110:113], v[158:161], v[214:217], v[110:113]
	v_mfma_f32_16x16x32_bf16 v[102:105], v[166:169], v[214:217], v[102:105]
	v_mfma_f32_16x16x32_bf16 v[94:97], v[158:161], v[222:225], v[94:97]
	v_mfma_f32_16x16x32_bf16 v[86:89], v[166:169], v[222:225], v[86:89]
	v_mfma_f32_16x16x32_bf16 v[78:81], v[158:161], v[230:233], v[78:81]
	v_mfma_f32_16x16x32_bf16 v[70:73], v[166:169], v[230:233], v[70:73]
	s_setprio 0
	s_setprio 1
	v_mfma_f32_16x16x32_bf16 v[122:125], v[170:173], v[202:205], v[122:125]
	v_mfma_f32_16x16x32_bf16 v[114:117], v[182:185], v[202:205], v[114:117]
	v_mfma_f32_16x16x32_bf16 v[106:109], v[170:173], v[210:213], v[106:109]
	v_mfma_f32_16x16x32_bf16 v[98:101], v[182:185], v[210:213], v[98:101]
	v_mfma_f32_16x16x32_bf16 v[90:93], v[170:173], v[218:221], v[90:93]
	v_mfma_f32_16x16x32_bf16 v[82:85], v[182:185], v[218:221], v[82:85]
	v_mfma_f32_16x16x32_bf16 v[74:77], v[170:173], v[226:229], v[74:77]
	v_mfma_f32_16x16x32_bf16 v[66:69], v[182:185], v[226:229], v[66:69]
	v_mfma_f32_16x16x32_bf16 v[122:125], v[174:177], v[206:209], v[122:125]
	v_mfma_f32_16x16x32_bf16 v[114:117], v[198:201], v[206:209], v[114:117]
	v_mfma_f32_16x16x32_bf16 v[106:109], v[174:177], v[214:217], v[106:109]
	v_mfma_f32_16x16x32_bf16 v[98:101], v[198:201], v[214:217], v[98:101]
	v_mfma_f32_16x16x32_bf16 v[90:93], v[174:177], v[222:225], v[90:93]
	v_mfma_f32_16x16x32_bf16 v[82:85], v[198:201], v[222:225], v[82:85]
	v_mfma_f32_16x16x32_bf16 v[74:77], v[174:177], v[230:233], v[74:77]
	v_mfma_f32_16x16x32_bf16 v[66:69], v[198:201], v[230:233], v[66:69]
	s_setprio 0
	s_barrier
	ds_read_b128 v[202:205], v146 offset:16384
	ds_read_b128 v[206:209], v146 offset:17408
	ds_read_b128 v[210:213], v146 offset:18432
	ds_read_b128 v[214:217], v146 offset:19456
	ds_read_b128 v[218:221], v146 offset:20480
	ds_read_b128 v[222:225], v146 offset:21504
	ds_read_b128 v[226:229], v146 offset:22528
	ds_read_b128 v[230:233], v146 offset:23552
	s_add_i32 s25, s25, s61
	v_lshl_add_u64 v[140:141], s[22:23], 0, v[0:1]
	s_mov_b32 m0, s25
	s_nop 0
	global_load_lds_dwordx4 v[140:141], off
	s_add_i32 m0, s25, 0x2000
	v_lshl_add_u64 v[234:235], s[22:23], 0, v[130:131]
	s_add_u32 s22, s22, s28
	s_addc_u32 s23, s23, 0
	s_add_i32 s21, s21, s61
	global_load_lds_dwordx4 v[234:235], off
	v_lshl_add_u64 v[236:237], s[22:23], 0, v[0:1]
	s_mov_b32 m0, s21
	v_lshl_add_u64 v[238:239], s[22:23], 0, v[130:131]
	global_load_lds_dwordx4 v[236:237], off
	s_add_i32 m0, s21, 0x2000
	v_lshl_add_u64 v[240:241], s[18:19], 0, v[134:135]
	global_load_lds_dwordx4 v[238:239], off
	s_mov_b32 m0, s68
	v_lshl_add_u64 v[242:243], s[18:19], 0, v[132:133]
	global_load_lds_dwordx4 v[240:241], off
	s_mov_b32 m0, s69
	s_nop 0
	global_load_lds_dwordx4 v[242:243], off
	s_waitcnt vmcnt(8)
	s_waitcnt lgkmcnt(0)
	s_barrier
; #define PG8_STAGE(bufoff, gbase, voff) do { _Pragma("unroll") for (int _i = 0; _i < 2; ++_i) \
;         __builtin_amdgcn_global_load_lds((const unsigned*)((const char*)(gbase) + (voff)[_i]), (PG8_LAS unsigned*)(lds + (bufoff) + ldsw + _i * 8192), 16, 0, 0); } while (0)
; #define PG8_LDA(dst, b, h) do { _Pragma("unroll") for (int m = 0; m < 4; ++m) _Pragma("unroll") for (int k = 0; k < 2; ++k) dst[m][k] = *(const PG8_LAS bf16x8*)(lds + PG8_SA(b, h) + aoff + m * 2048 + k * 1024); } while (0)
; #define PG8_LDB(dst, b, h) do { _Pragma("unroll") for (int n = 0; n < 2; ++n) _Pragma("unroll") for (int k = 0; k < 2; ++k) dst[n][k] = *(const PG8_LAS bf16x8*)(lds + PG8_SB(b, h) + boff + n * 2048 + k * 1024); } while (0)
; #define PG8_MMA(ai, bj, At, Bt) do { __builtin_amdgcn_s_setprio(1); _Pragma("unroll") for (int m = 0; m < 4; ++m) _Pragma("unroll") for (int n = 0; n < 2; ++n) _Pragma("unroll") for (int k = 0; k < 2; ++k) \
;         acc[ai][bj][m][n] = __builtin_amdgcn_mfma_f32_16x16x32_bf16(Bt[n][k], At[m][k], acc[ai][bj][m][n], 0, 0, 0); __builtin_amdgcn_s_setprio(0); } while (0)
; #define PG8_WAIT_V(n) asm volatile("s_waitcnt vmcnt(" #n ")" ::: "memory")
; #define PG8_WAIT_L(n) asm volatile("s_waitcnt lgkmcnt(" #n ")" ::: "memory")
; #define PG8_BAR __builtin_amdgcn_s_barrier()
; #define PG8_SCHED __builtin_amdgcn_sched_barrier(0)
; template <class Epi, class Sched, bool ALIGN_EPI = false, bool SP2 = false>
; __device__ __forceinline__ void gemm_phase(PG8_LAS unsigned char* lds, const Gemm g, const Sched S, const Epi E) {
;     ...
;             PG8_WAIT_V(8); PG8_WAIT_L(0); PG8_BAR; PG8_MMA(1, 0, At, B0); PG8_MMA(1, 1, At, B1); PG8_BAR; PG8_SCHED;
;             PG8_LDB(B0, 1, 0); PG8_LDB(B1, 1, 1); PG8_SCHED; PG8_LDA(At, 1, 0); PG8_STAGE(PG8_SA(0, 1), a2 + hstep, voffA);
;             PG8_WAIT_V(8); PG8_WAIT_L(0); PG8_BAR; PG8_MMA(0, 0, At, B0); PG8_MMA(0, 1, At, B1); PG8_BAR; PG8_SCHED;
	s_setprio 1
	s_waitcnt lgkmcnt(0)
	v_mfma_f32_16x16x32_bf16 v[62:65], v[154:157], v[202:205], v[62:65]
	v_mfma_f32_16x16x32_bf16 v[54:57], v[162:165], v[202:205], v[54:57]
	v_mfma_f32_16x16x32_bf16 v[46:49], v[154:157], v[210:213], v[46:49]
	v_mfma_f32_16x16x32_bf16 v[38:41], v[162:165], v[210:213], v[38:41]
	v_mfma_f32_16x16x32_bf16 v[30:33], v[154:157], v[218:221], v[30:33]
	v_mfma_f32_16x16x32_bf16 v[22:25], v[162:165], v[218:221], v[22:25]
	v_mfma_f32_16x16x32_bf16 v[14:17], v[154:157], v[226:229], v[14:17]
	v_mfma_f32_16x16x32_bf16 v[6:9], v[162:165], v[226:229], v[6:9]
	v_mfma_f32_16x16x32_bf16 v[62:65], v[158:161], v[206:209], v[62:65]
	v_mfma_f32_16x16x32_bf16 v[54:57], v[166:169], v[206:209], v[54:57]
	v_mfma_f32_16x16x32_bf16 v[46:49], v[158:161], v[214:217], v[46:49]
	v_mfma_f32_16x16x32_bf16 v[38:41], v[166:169], v[214:217], v[38:41]
	v_mfma_f32_16x16x32_bf16 v[30:33], v[158:161], v[222:225], v[30:33]
	v_mfma_f32_16x16x32_bf16 v[22:25], v[166:169], v[222:225], v[22:25]
	v_mfma_f32_16x16x32_bf16 v[14:17], v[158:161], v[230:233], v[14:17]
	v_mfma_f32_16x16x32_bf16 v[6:9], v[166:169], v[230:233], v[6:9]
	s_setprio 0
	s_setprio 1
	v_mfma_f32_16x16x32_bf16 v[58:61], v[170:173], v[202:205], v[58:61]
	v_mfma_f32_16x16x32_bf16 v[50:53], v[182:185], v[202:205], v[50:53]
	v_mfma_f32_16x16x32_bf16 v[42:45], v[170:173], v[210:213], v[42:45]
	v_mfma_f32_16x16x32_bf16 v[34:37], v[182:185], v[210:213], v[34:37]
	v_mfma_f32_16x16x32_bf16 v[26:29], v[170:173], v[218:221], v[26:29]
	v_mfma_f32_16x16x32_bf16 v[18:21], v[182:185], v[218:221], v[18:21]
	v_mfma_f32_16x16x32_bf16 v[10:13], v[170:173], v[226:229], v[10:13]
	v_mfma_f32_16x16x32_bf16 v[2:5], v[182:185], v[226:229], v[2:5]
	v_mfma_f32_16x16x32_bf16 v[58:61], v[174:177], v[206:209], v[58:61]
	v_mfma_f32_16x16x32_bf16 v[50:53], v[198:201], v[206:209], v[50:53]
	v_mfma_f32_16x16x32_bf16 v[42:45], v[174:177], v[214:217], v[42:45]
	v_mfma_f32_16x16x32_bf16 v[34:37], v[198:201], v[214:217], v[34:37]
	v_mfma_f32_16x16x32_bf16 v[26:29], v[174:177], v[222:225], v[26:29]
	v_mfma_f32_16x16x32_bf16 v[18:21], v[198:201], v[222:225], v[18:21]
	v_mfma_f32_16x16x32_bf16 v[10:13], v[174:177], v[230:233], v[10:13]
	v_mfma_f32_16x16x32_bf16 v[2:5], v[198:201], v[230:233], v[2:5]
	s_setprio 0
	s_barrier
	v_add_u32_e32 v166, 0x18000, v143
	v_add_u32_e32 v186, 0x1c000, v143
	ds_read_b128 v[154:157], v166
	ds_read_b128 v[158:161], v166 offset:1024
	ds_read_b128 v[162:165], v166 offset:2048
	ds_read_b128 v[166:169], v166 offset:3072
	ds_read_b128 v[170:173], v186
	ds_read_b128 v[174:177], v186 offset:1024
	ds_read_b128 v[182:185], v186 offset:2048
	ds_read_b128 v[198:201], v186 offset:3072
	ds_read_b128 v[202:205], v146 offset:32768
	ds_read_b128 v[206:209], v146 offset:33792
	ds_read_b128 v[210:213], v146 offset:34816
	ds_read_b128 v[214:217], v146 offset:35840
	ds_read_b128 v[218:221], v146 offset:36864
	ds_read_b128 v[222:225], v146 offset:37888
	ds_read_b128 v[226:229], v146 offset:38912
	ds_read_b128 v[230:233], v146 offset:39936
	s_add_i32 s21, 0, 0x18000
	s_add_i32 s22, 0, 0x1c000
	s_add_u32 s18, s18, s28
	s_addc_u32 s19, s19, 0
	s_mov_b32 m0, s70
	v_lshl_add_u64 v[244:245], s[18:19], 0, v[134:135]
	global_load_lds_dwordx4 v[244:245], off
	v_lshl_add_u64 v[244:245], s[18:19], 0, v[132:133]
	s_mov_b32 m0, s71
	s_nop 0
	global_load_lds_dwordx4 v[244:245], off
	s_waitcnt vmcnt(8)
	s_waitcnt lgkmcnt(0)
	s_barrier
	s_setprio 1
	s_waitcnt lgkmcnt(0)
	v_mfma_f32_16x16x32_bf16 v[126:129], v[154:157], v[202:205], v[126:129]
	v_mfma_f32_16x16x32_bf16 v[118:121], v[162:165], v[202:205], v[118:121]
	v_mfma_f32_16x16x32_bf16 v[110:113], v[154:157], v[210:213], v[110:113]
	v_mfma_f32_16x16x32_bf16 v[102:105], v[162:165], v[210:213], v[102:105]
	v_mfma_f32_16x16x32_bf16 v[94:97], v[154:157], v[218:221], v[94:97]
	v_mfma_f32_16x16x32_bf16 v[86:89], v[162:165], v[218:221], v[86:89]
	v_mfma_f32_16x16x32_bf16 v[78:81], v[154:157], v[226:229], v[78:81]
	v_mfma_f32_16x16x32_bf16 v[70:73], v[162:165], v[226:229], v[70:73]
	v_mfma_f32_16x16x32_bf16 v[126:129], v[158:161], v[206:209], v[126:129]
	v_mfma_f32_16x16x32_bf16 v[118:121], v[166:169], v[206:209], v[118:121]
	v_mfma_f32_16x16x32_bf16 v[110:113], v[158:161], v[214:217], v[110:113]
	v_mfma_f32_16x16x32_bf16 v[102:105], v[166:169], v[214:217], v[102:105]
	v_mfma_f32_16x16x32_bf16 v[94:97], v[158:161], v[222:225], v[94:97]
	v_mfma_f32_16x16x32_bf16 v[86:89], v[166:169], v[222:225], v[86:89]
	v_mfma_f32_16x16x32_bf16 v[78:81], v[158:161], v[230:233], v[78:81]
	v_mfma_f32_16x16x32_bf16 v[70:73], v[166:169], v[230:233], v[70:73]
	s_setprio 0
	s_setprio 1
	v_mfma_f32_16x16x32_bf16 v[122:125], v[170:173], v[202:205], v[122:125]
	v_mfma_f32_16x16x32_bf16 v[114:117], v[182:185], v[202:205], v[114:117]
	v_mfma_f32_16x16x32_bf16 v[106:109], v[170:173], v[210:213], v[106:109]
	v_mfma_f32_16x16x32_bf16 v[98:101], v[182:185], v[210:213], v[98:101]
	v_mfma_f32_16x16x32_bf16 v[90:93], v[170:173], v[218:221], v[90:93]
	v_mfma_f32_16x16x32_bf16 v[82:85], v[182:185], v[218:221], v[82:85]
	v_mfma_f32_16x16x32_bf16 v[74:77], v[170:173], v[226:229], v[74:77]
	v_mfma_f32_16x16x32_bf16 v[66:69], v[182:185], v[226:229], v[66:69]
	v_mfma_f32_16x16x32_bf16 v[122:125], v[174:177], v[206:209], v[122:125]
	v_mfma_f32_16x16x32_bf16 v[114:117], v[198:201], v[206:209], v[114:117]
	v_mfma_f32_16x16x32_bf16 v[106:109], v[174:177], v[214:217], v[106:109]
	v_mfma_f32_16x16x32_bf16 v[98:101], v[198:201], v[214:217], v[98:101]
	v_mfma_f32_16x16x32_bf16 v[90:93], v[174:177], v[222:225], v[90:93]
	v_mfma_f32_16x16x32_bf16 v[82:85], v[198:201], v[222:225], v[82:85]
	v_mfma_f32_16x16x32_bf16 v[74:77], v[174:177], v[230:233], v[74:77]
	v_mfma_f32_16x16x32_bf16 v[66:69], v[198:201], v[230:233], v[66:69]
	s_setprio 0
	s_barrier
; #define PG8_STAGE(bufoff, gbase, voff) do { _Pragma("unroll") for (int _i = 0; _i < 2; ++_i) \
;         __builtin_amdgcn_global_load_lds((const unsigned*)((const char*)(gbase) + (voff)[_i]), (PG8_LAS unsigned*)(lds + (bufoff) + ldsw + _i * 8192), 16, 0, 0); } while (0)
; #define PG8_LDA(dst, b, h) do { _Pragma("unroll") for (int m = 0; m < 4; ++m) _Pragma("unroll") for (int k = 0; k < 2; ++k) dst[m][k] = *(const PG8_LAS bf16x8*)(lds + PG8_SA(b, h) + aoff + m * 2048 + k * 1024); } while (0)
; #define PG8_MMA(ai, bj, At, Bt) do { __builtin_amdgcn_s_setprio(1); _Pragma("unroll") for (int m = 0; m < 4; ++m) _Pragma("unroll") for (int n = 0; n < 2; ++n) _Pragma("unroll") for (int k = 0; k < 2; ++k) \
;         acc[ai][bj][m][n] = __builtin_amdgcn_mfma_f32_16x16x32_bf16(Bt[n][k], At[m][k], acc[ai][bj][m][n], 0, 0, 0); __builtin_amdgcn_s_setprio(0); } while (0)
; #define PG8_WAIT_V(n) asm volatile("s_waitcnt vmcnt(" #n ")" ::: "memory")
; #define PG8_WAIT_L(n) asm volatile("s_waitcnt lgkmcnt(" #n ")" ::: "memory")
; #define PG8_BAR __builtin_amdgcn_s_barrier()
; #define PG8_SCHED __builtin_amdgcn_sched_barrier(0)
; template <class Epi, class Sched, bool ALIGN_EPI = false, bool SP2 = false>
; __device__ __forceinline__ void gemm_phase(PG8_LAS unsigned char* lds, const Gemm g, const Sched S, const Epi E) {
;     ...
;             PG8_LDA(At, 1, 1); PG8_STAGE(PG8_SB(1, 0), b3, voffB); PG8_STAGE(PG8_SB(1, 1), b3 + hstep, voffB); PG8_STAGE(PG8_SA(1, 0), a3, voffA);
;             PG8_WAIT_V(8); PG8_WAIT_L(0); PG8_BAR; PG8_MMA(1, 0, At, B0); PG8_MMA(1, 1, At, B1); PG8_BAR; PG8_SCHED;
;     ...
;         }
;         if constexpr (ALIGN_EPI) { if (wr == 0) PG8_BAR; }
	ds_read_b128 v[202:205], v146 offset:49152
	ds_read_b128 v[206:209], v146 offset:50176
	ds_read_b128 v[210:213], v146 offset:51200
	ds_read_b128 v[214:217], v146 offset:52224
	ds_read_b128 v[218:221], v146 offset:53248
	ds_read_b128 v[222:225], v146 offset:54272
	ds_read_b128 v[226:229], v146 offset:55296
	ds_read_b128 v[230:233], v146 offset:56320
	s_add_i32 s18, s21, s61
	v_lshl_add_u64 v[140:141], v[140:141], 0, s[12:13]
	s_mov_b32 m0, s18
	s_nop 0
	global_load_lds_dwordx4 v[140:141], off
	v_lshl_add_u64 v[140:141], v[234:235], 0, s[12:13]
	s_add_i32 m0, s18, 0x2000
	s_add_i32 s18, s22, s61
	global_load_lds_dwordx4 v[140:141], off
	v_lshl_add_u64 v[140:141], v[236:237], 0, s[12:13]
	s_mov_b32 m0, s18
	s_nop 0
	global_load_lds_dwordx4 v[140:141], off
	v_lshl_add_u64 v[140:141], v[238:239], 0, s[12:13]
	s_add_i32 m0, s18, 0x2000
	s_nop 0
	global_load_lds_dwordx4 v[140:141], off
	v_lshl_add_u64 v[140:141], v[240:241], 0, s[12:13]
	s_mov_b32 m0, s73
	s_nop 0
	global_load_lds_dwordx4 v[140:141], off
	v_lshl_add_u64 v[140:141], v[242:243], 0, s[12:13]
	s_mov_b32 m0, s74
	s_nop 0
	global_load_lds_dwordx4 v[140:141], off
	s_waitcnt vmcnt(8)
	s_waitcnt lgkmcnt(0)
	s_barrier
	s_setprio 1
	s_waitcnt lgkmcnt(0)
	v_mfma_f32_16x16x32_bf16 v[62:65], v[154:157], v[202:205], v[62:65]
	v_mfma_f32_16x16x32_bf16 v[54:57], v[162:165], v[202:205], v[54:57]
	v_mfma_f32_16x16x32_bf16 v[46:49], v[154:157], v[210:213], v[46:49]
	v_mfma_f32_16x16x32_bf16 v[38:41], v[162:165], v[210:213], v[38:41]
	v_mfma_f32_16x16x32_bf16 v[30:33], v[154:157], v[218:221], v[30:33]
	v_mfma_f32_16x16x32_bf16 v[22:25], v[162:165], v[218:221], v[22:25]
	v_mfma_f32_16x16x32_bf16 v[14:17], v[154:157], v[226:229], v[14:17]
	v_mfma_f32_16x16x32_bf16 v[6:9], v[162:165], v[226:229], v[6:9]
	v_mfma_f32_16x16x32_bf16 v[62:65], v[158:161], v[206:209], v[62:65]
	v_mfma_f32_16x16x32_bf16 v[54:57], v[166:169], v[206:209], v[54:57]
	v_mfma_f32_16x16x32_bf16 v[46:49], v[158:161], v[214:217], v[46:49]
	v_mfma_f32_16x16x32_bf16 v[38:41], v[166:169], v[214:217], v[38:41]
	v_mfma_f32_16x16x32_bf16 v[30:33], v[158:161], v[222:225], v[30:33]
	v_mfma_f32_16x16x32_bf16 v[22:25], v[166:169], v[222:225], v[22:25]
	v_mfma_f32_16x16x32_bf16 v[14:17], v[158:161], v[230:233], v[14:17]
	v_mfma_f32_16x16x32_bf16 v[6:9], v[166:169], v[230:233], v[6:9]
	s_setprio 0
	s_setprio 1
	v_mfma_f32_16x16x32_bf16 v[58:61], v[170:173], v[202:205], v[58:61]
	v_mfma_f32_16x16x32_bf16 v[50:53], v[182:185], v[202:205], v[50:53]
	v_mfma_f32_16x16x32_bf16 v[42:45], v[170:173], v[210:213], v[42:45]
	v_mfma_f32_16x16x32_bf16 v[34:37], v[182:185], v[210:213], v[34:37]
	v_mfma_f32_16x16x32_bf16 v[26:29], v[170:173], v[218:221], v[26:29]
	v_mfma_f32_16x16x32_bf16 v[18:21], v[182:185], v[218:221], v[18:21]
	v_mfma_f32_16x16x32_bf16 v[10:13], v[170:173], v[226:229], v[10:13]
	v_mfma_f32_16x16x32_bf16 v[2:5], v[182:185], v[226:229], v[2:5]
	v_mfma_f32_16x16x32_bf16 v[58:61], v[174:177], v[206:209], v[58:61]
	v_mfma_f32_16x16x32_bf16 v[50:53], v[198:201], v[206:209], v[50:53]
	v_mfma_f32_16x16x32_bf16 v[42:45], v[174:177], v[214:217], v[42:45]
	v_mfma_f32_16x16x32_bf16 v[34:37], v[198:201], v[214:217], v[34:37]
	v_mfma_f32_16x16x32_bf16 v[26:29], v[174:177], v[222:225], v[26:29]
	v_mfma_f32_16x16x32_bf16 v[18:21], v[198:201], v[222:225], v[18:21]
	v_mfma_f32_16x16x32_bf16 v[10:13], v[174:177], v[230:233], v[10:13]
	v_mfma_f32_16x16x32_bf16 v[2:5], v[198:201], v[230:233], v[2:5]
	s_setprio 0
	s_add_u32 s16, s16, 0x100
	s_addc_u32 s17, s17, 0
	s_add_u32 s14, s14, 0x100
	s_addc_u32 s15, s15, 0
	s_cmp_ge_u32 s20, s72
	s_mov_b32 s18, s20
	s_barrier
	s_cbranch_scc0 .LBB0_180
	s_and_b64 vcc, exec, s[56:57]
	s_cbranch_vccz .LBB0_183
	s_barrier

; #define PG8_STAGE(bufoff, gbase, voff) do { _Pragma("unroll") for (int _i = 0; _i < 2; ++_i) \
;         __builtin_amdgcn_global_load_lds((const unsigned*)((const char*)(gbase) + (voff)[_i]), (PG8_LAS unsigned*)(lds + (bufoff) + ldsw + _i * 8192), 16, 0, 0); } while (0)
; #define PG8_LDA(dst, b, h) do { _Pragma("unroll") for (int m = 0; m < 4; ++m) _Pragma("unroll") for (int k = 0; k < 2; ++k) dst[m][k] = *(const PG8_LAS bf16x8*)(lds + PG8_SA(b, h) + aoff + m * 2048 + k * 1024); } while (0)
; #define PG8_LDB(dst, b, h) do { _Pragma("unroll") for (int n = 0; n < 2; ++n) _Pragma("unroll") for (int k = 0; k < 2; ++k) dst[n][k] = *(const PG8_LAS bf16x8*)(lds + PG8_SB(b, h) + boff + n * 2048 + k * 1024); } while (0)
; #define PG8_MMA(ai, bj, At, Bt) do { __builtin_amdgcn_s_setprio(1); _Pragma("unroll") for (int m = 0; m < 4; ++m) _Pragma("unroll") for (int n = 0; n < 2; ++n) _Pragma("unroll") for (int k = 0; k < 2; ++k) \
;         acc[ai][bj][m][n] = __builtin_amdgcn_mfma_f32_16x16x32_bf16(Bt[n][k], At[m][k], acc[ai][bj][m][n], 0, 0, 0); __builtin_amdgcn_s_setprio(0); } while (0)
; #define PG8_WAIT_V(n) asm volatile("s_waitcnt vmcnt(" #n ")" ::: "memory")
; #define PG8_WAIT_L(n) asm volatile("s_waitcnt lgkmcnt(" #n ")" ::: "memory")
; #define PG8_BAR __builtin_amdgcn_s_barrier()
; #define PG8_SCHED __builtin_amdgcn_sched_barrier(0)
; template <class Epi, class Sched, bool ALIGN_EPI = false, bool SP2 = false>
; __device__ __forceinline__ void gemm_phase(PG8_LAS unsigned char* lds, const Gemm g, const Sched S, const Epi E) {
;     ...
;             const bool last = (t == nt - 2);
;             const char* a1 = cA + (size_t)(t + 1) * kstep;
;             const char* a2 = last ? nA : cA + (size_t)(t + 2) * kstep; const char* b2 = last ? nB : cB + (size_t)(t + 2) * kstep;
;             const char* a3 = a2 + kstep; const char* b3 = b2 + kstep;
;             if (last && has_next) S.a_ready(nxt);
;             if constexpr (SP2) {
;             PG8_LDB(B0, 0, 0); PG8_LDB(B1, 0, 1); PG8_SCHED; PG8_LDA(At, 0, 0); PG8_STAGE(PG8_SA(1, 1), a1 + hstep, voffA);
;             PG8_WAIT_V(8); PG8_WAIT_L(0); PG8_BAR; PG8_MMA(0, 0, At, B0); PG8_MMA(0, 1, At, B1); PG8_BAR; PG8_SCHED;
;             PG8_LDA(At, 0, 1); PG8_STAGE(PG8_SB(0, 0), b2, voffB); PG8_STAGE(PG8_SB(0, 1), b2 + hstep, voffB); PG8_STAGE(PG8_SA(0, 0), a2, voffA);
.LBB0_224:
	v_add_u32_e32 v141, 0x10000, v147
	ds_read_b128 v[154:157], v141
	ds_read_b128 v[158:161], v141 offset:1024
	ds_read_b128 v[162:165], v141 offset:2048
	ds_read_b128 v[166:169], v141 offset:3072
	v_add_u32_e32 v141, 0x14000, v147
	ds_read_b128 v[170:173], v141
	ds_read_b128 v[174:177], v141 offset:1024
	ds_read_b128 v[182:185], v141 offset:2048
	ds_read_b128 v[198:201], v141 offset:3072
	ds_read_b128 v[202:205], v152
	ds_read_b128 v[206:209], v152 offset:1024
	ds_read_b128 v[210:213], v152 offset:2048
	ds_read_b128 v[214:217], v152 offset:3072
	ds_read_b128 v[218:221], v152 offset:4096
	ds_read_b128 v[222:225], v152 offset:5120
	ds_read_b128 v[226:229], v152 offset:6144
	ds_read_b128 v[230:233], v152 offset:7168
	s_add_i32 s21, s20, 2
	s_add_u32 s22, s30, 0x80
	s_addc_u32 s23, s31, 0
	s_add_i32 s26, 0, 0x10000
	s_cmp_eq_u32 s81, s20
	s_cselect_b32 s75, s1, s23
	s_cselect_b32 s74, s0, s22
	s_cselect_b32 s23, s19, s15
	s_cselect_b32 s22, s18, s14
	s_add_i32 s20, 0, 0x14000
	v_lshl_add_u64 v[234:235], s[30:31], 0, v[136:137]
	s_add_i32 m0, s85, 0xc000
	s_nop 0
	global_load_lds_dwordx4 v[234:235], off
	v_lshl_add_u64 v[234:235], s[30:31], 0, v[138:139]
	s_add_i32 m0, s85, 0xe000
	s_nop 0
	global_load_lds_dwordx4 v[234:235], off
	s_waitcnt vmcnt(8)
	s_waitcnt lgkmcnt(0)
	s_barrier
	s_setprio 1
	s_waitcnt lgkmcnt(0)
	v_mfma_f32_16x16x32_bf16 v[126:129], v[154:157], v[202:205], v[126:129]
	v_mfma_f32_16x16x32_bf16 v[122:125], v[162:165], v[202:205], v[122:125]
	v_mfma_f32_16x16x32_bf16 v[110:113], v[154:157], v[210:213], v[110:113]
	v_mfma_f32_16x16x32_bf16 v[106:109], v[162:165], v[210:213], v[106:109]
	v_mfma_f32_16x16x32_bf16 v[94:97], v[154:157], v[218:221], v[94:97]
	v_mfma_f32_16x16x32_bf16 v[90:93], v[162:165], v[218:221], v[90:93]
	v_mfma_f32_16x16x32_bf16 v[78:81], v[154:157], v[226:229], v[78:81]
	v_mfma_f32_16x16x32_bf16 v[74:77], v[162:165], v[226:229], v[74:77]
	v_mfma_f32_16x16x32_bf16 v[126:129], v[158:161], v[206:209], v[126:129]
	v_mfma_f32_16x16x32_bf16 v[122:125], v[166:169], v[206:209], v[122:125]
	v_mfma_f32_16x16x32_bf16 v[110:113], v[158:161], v[214:217], v[110:113]
	v_mfma_f32_16x16x32_bf16 v[106:109], v[166:169], v[214:217], v[106:109]
	v_mfma_f32_16x16x32_bf16 v[94:97], v[158:161], v[222:225], v[94:97]
	v_mfma_f32_16x16x32_bf16 v[90:93], v[166:169], v[222:225], v[90:93]
	v_mfma_f32_16x16x32_bf16 v[78:81], v[158:161], v[230:233], v[78:81]
	v_mfma_f32_16x16x32_bf16 v[74:77], v[166:169], v[230:233], v[74:77]
	s_setprio 0
	s_setprio 1
	v_mfma_f32_16x16x32_bf16 v[118:121], v[170:173], v[202:205], v[118:121]
	v_mfma_f32_16x16x32_bf16 v[114:117], v[182:185], v[202:205], v[114:117]
	v_mfma_f32_16x16x32_bf16 v[102:105], v[170:173], v[210:213], v[102:105]
	v_mfma_f32_16x16x32_bf16 v[98:101], v[182:185], v[210:213], v[98:101]
	v_mfma_f32_16x16x32_bf16 v[86:89], v[170:173], v[218:221], v[86:89]
	v_mfma_f32_16x16x32_bf16 v[82:85], v[182:185], v[218:221], v[82:85]
	v_mfma_f32_16x16x32_bf16 v[70:73], v[170:173], v[226:229], v[70:73]
	v_mfma_f32_16x16x32_bf16 v[66:69], v[182:185], v[226:229], v[66:69]
	v_mfma_f32_16x16x32_bf16 v[118:121], v[174:177], v[206:209], v[118:121]
	v_mfma_f32_16x16x32_bf16 v[114:117], v[198:201], v[206:209], v[114:117]
	v_mfma_f32_16x16x32_bf16 v[102:105], v[174:177], v[214:217], v[102:105]
	v_mfma_f32_16x16x32_bf16 v[98:101], v[198:201], v[214:217], v[98:101]
	v_mfma_f32_16x16x32_bf16 v[86:89], v[174:177], v[222:225], v[86:89]
	v_mfma_f32_16x16x32_bf16 v[82:85], v[198:201], v[222:225], v[82:85]
	v_mfma_f32_16x16x32_bf16 v[70:73], v[174:177], v[230:233], v[70:73]
	v_mfma_f32_16x16x32_bf16 v[66:69], v[198:201], v[230:233], v[66:69]
	s_setprio 0
	s_barrier
	ds_read_b128 v[202:205], v152 offset:16384
	ds_read_b128 v[206:209], v152 offset:17408
	ds_read_b128 v[210:213], v152 offset:18432
	ds_read_b128 v[214:217], v152 offset:19456
	ds_read_b128 v[218:221], v152 offset:20480
	ds_read_b128 v[222:225], v152 offset:21504
	ds_read_b128 v[226:229], v152 offset:22528
	ds_read_b128 v[230:233], v152 offset:23552
	s_add_i32 s26, s26, s84
	v_lshl_add_u64 v[234:235], s[22:23], 0, v[0:1]
	s_mov_b32 m0, s26
	s_nop 0
	global_load_lds_dwordx4 v[234:235], off
	s_add_i32 m0, s26, 0x2000
	v_lshl_add_u64 v[236:237], s[22:23], 0, v[134:135]
	s_add_u32 s22, s22, s52
	s_addc_u32 s23, s23, 0
	s_add_i32 s20, s20, s84
	global_load_lds_dwordx4 v[236:237], off
	v_lshl_add_u64 v[238:239], s[22:23], 0, v[0:1]
	s_mov_b32 m0, s20
	v_lshl_add_u64 v[240:241], s[22:23], 0, v[134:135]
	global_load_lds_dwordx4 v[238:239], off
	s_add_i32 m0, s20, 0x2000
	v_lshl_add_u64 v[242:243], s[74:75], 0, v[130:131]
	global_load_lds_dwordx4 v[240:241], off
	s_mov_b32 m0, s85
	v_lshl_add_u64 v[244:245], s[74:75], 0, v[132:133]
	global_load_lds_dwordx4 v[242:243], off
	s_mov_b32 m0, s86
	s_nop 0
	global_load_lds_dwordx4 v[244:245], off
	s_waitcnt vmcnt(8)
	s_waitcnt lgkmcnt(0)
	s_barrier
; #define PG8_STAGE(bufoff, gbase, voff) do { _Pragma("unroll") for (int _i = 0; _i < 2; ++_i) \
;         __builtin_amdgcn_global_load_lds((const unsigned*)((const char*)(gbase) + (voff)[_i]), (PG8_LAS unsigned*)(lds + (bufoff) + ldsw + _i * 8192), 16, 0, 0); } while (0)
; #define PG8_LDA(dst, b, h) do { _Pragma("unroll") for (int m = 0; m < 4; ++m) _Pragma("unroll") for (int k = 0; k < 2; ++k) dst[m][k] = *(const PG8_LAS bf16x8*)(lds + PG8_SA(b, h) + aoff + m * 2048 + k * 1024); } while (0)
; #define PG8_LDB(dst, b, h) do { _Pragma("unroll") for (int n = 0; n < 2; ++n) _Pragma("unroll") for (int k = 0; k < 2; ++k) dst[n][k] = *(const PG8_LAS bf16x8*)(lds + PG8_SB(b, h) + boff + n * 2048 + k * 1024); } while (0)
; #define PG8_MMA(ai, bj, At, Bt) do { __builtin_amdgcn_s_setprio(1); _Pragma("unroll") for (int m = 0; m < 4; ++m) _Pragma("unroll") for (int n = 0; n < 2; ++n) _Pragma("unroll") for (int k = 0; k < 2; ++k) \
;         acc[ai][bj][m][n] = __builtin_amdgcn_mfma_f32_16x16x32_bf16(Bt[n][k], At[m][k], acc[ai][bj][m][n], 0, 0, 0); __builtin_amdgcn_s_setprio(0); } while (0)
; #define PG8_WAIT_V(n) asm volatile("s_waitcnt vmcnt(" #n ")" ::: "memory")
; #define PG8_WAIT_L(n) asm volatile("s_waitcnt lgkmcnt(" #n ")" ::: "memory")
; #define PG8_BAR __builtin_amdgcn_s_barrier()
; #define PG8_SCHED __builtin_amdgcn_sched_barrier(0)
; template <class Epi, class Sched, bool ALIGN_EPI = false, bool SP2 = false>
; __device__ __forceinline__ void gemm_phase(PG8_LAS unsigned char* lds, const Gemm g, const Sched S, const Epi E) {
;     ...
;             PG8_WAIT_V(8); PG8_WAIT_L(0); PG8_BAR; PG8_MMA(1, 0, At, B0); PG8_MMA(1, 1, At, B1); PG8_BAR; PG8_SCHED;
;             PG8_LDB(B0, 1, 0); PG8_LDB(B1, 1, 1); PG8_SCHED; PG8_LDA(At, 1, 0); PG8_STAGE(PG8_SA(0, 1), a2 + hstep, voffA);
;             PG8_WAIT_V(8); PG8_WAIT_L(0); PG8_BAR; PG8_MMA(0, 0, At, B0); PG8_MMA(0, 1, At, B1); PG8_BAR; PG8_SCHED;
	s_setprio 1
	s_waitcnt lgkmcnt(0)
	v_mfma_f32_16x16x32_bf16 v[62:65], v[154:157], v[202:205], v[62:65]
	v_mfma_f32_16x16x32_bf16 v[58:61], v[162:165], v[202:205], v[58:61]
	v_mfma_f32_16x16x32_bf16 v[46:49], v[154:157], v[210:213], v[46:49]
	v_mfma_f32_16x16x32_bf16 v[42:45], v[162:165], v[210:213], v[42:45]
	v_mfma_f32_16x16x32_bf16 v[30:33], v[154:157], v[218:221], v[30:33]
	v_mfma_f32_16x16x32_bf16 v[26:29], v[162:165], v[218:221], v[26:29]
	v_mfma_f32_16x16x32_bf16 v[14:17], v[154:157], v[226:229], v[14:17]
	v_mfma_f32_16x16x32_bf16 v[10:13], v[162:165], v[226:229], v[10:13]
	v_mfma_f32_16x16x32_bf16 v[62:65], v[158:161], v[206:209], v[62:65]
	v_mfma_f32_16x16x32_bf16 v[58:61], v[166:169], v[206:209], v[58:61]
	v_mfma_f32_16x16x32_bf16 v[46:49], v[158:161], v[214:217], v[46:49]
	v_mfma_f32_16x16x32_bf16 v[42:45], v[166:169], v[214:217], v[42:45]
	v_mfma_f32_16x16x32_bf16 v[30:33], v[158:161], v[222:225], v[30:33]
	v_mfma_f32_16x16x32_bf16 v[26:29], v[166:169], v[222:225], v[26:29]
	v_mfma_f32_16x16x32_bf16 v[14:17], v[158:161], v[230:233], v[14:17]
	v_mfma_f32_16x16x32_bf16 v[10:13], v[166:169], v[230:233], v[10:13]
	s_setprio 0
	s_setprio 1
	v_mfma_f32_16x16x32_bf16 v[54:57], v[170:173], v[202:205], v[54:57]
	v_mfma_f32_16x16x32_bf16 v[50:53], v[182:185], v[202:205], v[50:53]
	v_mfma_f32_16x16x32_bf16 v[38:41], v[170:173], v[210:213], v[38:41]
	v_mfma_f32_16x16x32_bf16 v[34:37], v[182:185], v[210:213], v[34:37]
	v_mfma_f32_16x16x32_bf16 v[22:25], v[170:173], v[218:221], v[22:25]
	v_mfma_f32_16x16x32_bf16 v[18:21], v[182:185], v[218:221], v[18:21]
	v_mfma_f32_16x16x32_bf16 v[6:9], v[170:173], v[226:229], v[6:9]
	v_mfma_f32_16x16x32_bf16 v[2:5], v[182:185], v[226:229], v[2:5]
	v_mfma_f32_16x16x32_bf16 v[54:57], v[174:177], v[206:209], v[54:57]
	v_mfma_f32_16x16x32_bf16 v[50:53], v[198:201], v[206:209], v[50:53]
	v_mfma_f32_16x16x32_bf16 v[38:41], v[174:177], v[214:217], v[38:41]
	v_mfma_f32_16x16x32_bf16 v[34:37], v[198:201], v[214:217], v[34:37]
	v_mfma_f32_16x16x32_bf16 v[22:25], v[174:177], v[222:225], v[22:25]
	v_mfma_f32_16x16x32_bf16 v[18:21], v[198:201], v[222:225], v[18:21]
	v_mfma_f32_16x16x32_bf16 v[6:9], v[174:177], v[230:233], v[6:9]
	v_mfma_f32_16x16x32_bf16 v[2:5], v[198:201], v[230:233], v[2:5]
	s_setprio 0
	s_barrier
	v_add_u32_e32 v141, 0x18000, v147
	ds_read_b128 v[154:157], v141
	ds_read_b128 v[158:161], v141 offset:1024
	ds_read_b128 v[162:165], v141 offset:2048
	ds_read_b128 v[166:169], v141 offset:3072
	v_add_u32_e32 v141, 0x1c000, v147
	ds_read_b128 v[170:173], v141
	ds_read_b128 v[174:177], v141 offset:1024
	ds_read_b128 v[182:185], v141 offset:2048
	ds_read_b128 v[198:201], v141 offset:3072
	ds_read_b128 v[202:205], v152 offset:32768
	ds_read_b128 v[206:209], v152 offset:33792
	ds_read_b128 v[210:213], v152 offset:34816
	ds_read_b128 v[214:217], v152 offset:35840
	ds_read_b128 v[218:221], v152 offset:36864
	ds_read_b128 v[222:225], v152 offset:37888
	ds_read_b128 v[226:229], v152 offset:38912
	ds_read_b128 v[230:233], v152 offset:39936
	s_add_i32 s20, 0, 0x18000
	s_add_i32 s26, 0, 0x1c000
	s_add_u32 s22, s74, s52
	s_addc_u32 s23, s75, 0
	s_mov_b32 m0, s87
	v_lshl_add_u64 v[246:247], s[22:23], 0, v[130:131]
	global_load_lds_dwordx4 v[246:247], off
	v_lshl_add_u64 v[246:247], s[22:23], 0, v[132:133]
	s_mov_b32 m0, s88
	s_nop 0
	global_load_lds_dwordx4 v[246:247], off
	s_waitcnt vmcnt(8)
	s_waitcnt lgkmcnt(0)
	s_barrier
	s_setprio 1
	s_waitcnt lgkmcnt(0)
	v_mfma_f32_16x16x32_bf16 v[126:129], v[154:157], v[202:205], v[126:129]
	v_mfma_f32_16x16x32_bf16 v[122:125], v[162:165], v[202:205], v[122:125]
	v_mfma_f32_16x16x32_bf16 v[110:113], v[154:157], v[210:213], v[110:113]
	v_mfma_f32_16x16x32_bf16 v[106:109], v[162:165], v[210:213], v[106:109]
	v_mfma_f32_16x16x32_bf16 v[94:97], v[154:157], v[218:221], v[94:97]
	v_mfma_f32_16x16x32_bf16 v[90:93], v[162:165], v[218:221], v[90:93]
	v_mfma_f32_16x16x32_bf16 v[78:81], v[154:157], v[226:229], v[78:81]
	v_mfma_f32_16x16x32_bf16 v[74:77], v[162:165], v[226:229], v[74:77]
	v_mfma_f32_16x16x32_bf16 v[126:129], v[158:161], v[206:209], v[126:129]
	v_mfma_f32_16x16x32_bf16 v[122:125], v[166:169], v[206:209], v[122:125]
	v_mfma_f32_16x16x32_bf16 v[110:113], v[158:161], v[214:217], v[110:113]
	v_mfma_f32_16x16x32_bf16 v[106:109], v[166:169], v[214:217], v[106:109]
	v_mfma_f32_16x16x32_bf16 v[94:97], v[158:161], v[222:225], v[94:97]
	v_mfma_f32_16x16x32_bf16 v[90:93], v[166:169], v[222:225], v[90:93]
	v_mfma_f32_16x16x32_bf16 v[78:81], v[158:161], v[230:233], v[78:81]
	v_mfma_f32_16x16x32_bf16 v[74:77], v[166:169], v[230:233], v[74:77]
	s_setprio 0
	s_setprio 1
	v_mfma_f32_16x16x32_bf16 v[118:121], v[170:173], v[202:205], v[118:121]
	v_mfma_f32_16x16x32_bf16 v[114:117], v[182:185], v[202:205], v[114:117]
	v_mfma_f32_16x16x32_bf16 v[102:105], v[170:173], v[210:213], v[102:105]
	v_mfma_f32_16x16x32_bf16 v[98:101], v[182:185], v[210:213], v[98:101]
	v_mfma_f32_16x16x32_bf16 v[86:89], v[170:173], v[218:221], v[86:89]
	v_mfma_f32_16x16x32_bf16 v[82:85], v[182:185], v[218:221], v[82:85]
	v_mfma_f32_16x16x32_bf16 v[70:73], v[170:173], v[226:229], v[70:73]
	v_mfma_f32_16x16x32_bf16 v[66:69], v[182:185], v[226:229], v[66:69]
	v_mfma_f32_16x16x32_bf16 v[118:121], v[174:177], v[206:209], v[118:121]
	v_mfma_f32_16x16x32_bf16 v[114:117], v[198:201], v[206:209], v[114:117]
	v_mfma_f32_16x16x32_bf16 v[102:105], v[174:177], v[214:217], v[102:105]
	v_mfma_f32_16x16x32_bf16 v[98:101], v[198:201], v[214:217], v[98:101]
	v_mfma_f32_16x16x32_bf16 v[86:89], v[174:177], v[222:225], v[86:89]
	v_mfma_f32_16x16x32_bf16 v[82:85], v[198:201], v[222:225], v[82:85]
	v_mfma_f32_16x16x32_bf16 v[70:73], v[174:177], v[230:233], v[70:73]
	v_mfma_f32_16x16x32_bf16 v[66:69], v[198:201], v[230:233], v[66:69]
	s_setprio 0
	s_barrier
; #define PG8_STAGE(bufoff, gbase, voff) do { _Pragma("unroll") for (int _i = 0; _i < 2; ++_i) \
;         __builtin_amdgcn_global_load_lds((const unsigned*)((const char*)(gbase) + (voff)[_i]), (PG8_LAS unsigned*)(lds + (bufoff) + ldsw + _i * 8192), 16, 0, 0); } while (0)
; #define PG8_LDA(dst, b, h) do { _Pragma("unroll") for (int m = 0; m < 4; ++m) _Pragma("unroll") for (int k = 0; k < 2; ++k) dst[m][k] = *(const PG8_LAS bf16x8*)(lds + PG8_SA(b, h) + aoff + m * 2048 + k * 1024); } while (0)
; #define PG8_MMA(ai, bj, At, Bt) do { __builtin_amdgcn_s_setprio(1); _Pragma("unroll") for (int m = 0; m < 4; ++m) _Pragma("unroll") for (int n = 0; n < 2; ++n) _Pragma("unroll") for (int k = 0; k < 2; ++k) \
;         acc[ai][bj][m][n] = __builtin_amdgcn_mfma_f32_16x16x32_bf16(Bt[n][k], At[m][k], acc[ai][bj][m][n], 0, 0, 0); __builtin_amdgcn_s_setprio(0); } while (0)
; #define PG8_WAIT_V(n) asm volatile("s_waitcnt vmcnt(" #n ")" ::: "memory")
; #define PG8_WAIT_L(n) asm volatile("s_waitcnt lgkmcnt(" #n ")" ::: "memory")
; #define PG8_BAR __builtin_amdgcn_s_barrier()
; #define PG8_SCHED __builtin_amdgcn_sched_barrier(0)
; template <class Epi, class Sched, bool ALIGN_EPI = false, bool SP2 = false>
; __device__ __forceinline__ void gemm_phase(PG8_LAS unsigned char* lds, const Gemm g, const Sched S, const Epi E) {
;     ...
;             PG8_LDA(At, 1, 1); PG8_STAGE(PG8_SB(1, 0), b3, voffB); PG8_STAGE(PG8_SB(1, 1), b3 + hstep, voffB); PG8_STAGE(PG8_SA(1, 0), a3, voffA);
;             PG8_WAIT_V(8); PG8_WAIT_L(0); PG8_BAR; PG8_MMA(1, 0, At, B0); PG8_MMA(1, 1, At, B1); PG8_BAR; PG8_SCHED;
;     ...
;         }
;         if constexpr (ALIGN_EPI) { if (wr == 0) PG8_BAR; }
	ds_read_b128 v[202:205], v152 offset:49152
	ds_read_b128 v[206:209], v152 offset:50176
	ds_read_b128 v[210:213], v152 offset:51200
	ds_read_b128 v[214:217], v152 offset:52224
	ds_read_b128 v[218:221], v152 offset:53248
	ds_read_b128 v[222:225], v152 offset:54272
	ds_read_b128 v[226:229], v152 offset:55296
	ds_read_b128 v[230:233], v152 offset:56320
	s_add_i32 s20, s20, s84
	v_lshl_add_u64 v[234:235], v[234:235], 0, s[12:13]
	s_mov_b32 m0, s20
	s_nop 0
	global_load_lds_dwordx4 v[234:235], off
	v_lshl_add_u64 v[234:235], v[236:237], 0, s[12:13]
	s_add_i32 m0, s20, 0x2000
	s_add_i32 s20, s26, s84
	global_load_lds_dwordx4 v[234:235], off
	v_lshl_add_u64 v[234:235], v[238:239], 0, s[12:13]
	s_mov_b32 m0, s20
	s_nop 0
	global_load_lds_dwordx4 v[234:235], off
	v_lshl_add_u64 v[234:235], v[240:241], 0, s[12:13]
	s_add_i32 m0, s20, 0x2000
	s_nop 0
	global_load_lds_dwordx4 v[234:235], off
	v_lshl_add_u64 v[234:235], v[242:243], 0, s[12:13]
	s_mov_b32 m0, s3
	s_nop 0
	global_load_lds_dwordx4 v[234:235], off
	v_lshl_add_u64 v[234:235], v[244:245], 0, s[12:13]
	s_mov_b32 m0, s24
	s_nop 0
	global_load_lds_dwordx4 v[234:235], off
	s_waitcnt vmcnt(8)
	s_waitcnt lgkmcnt(0)
	s_barrier
	s_setprio 1
	s_waitcnt lgkmcnt(0)
	v_mfma_f32_16x16x32_bf16 v[62:65], v[154:157], v[202:205], v[62:65]
	v_mfma_f32_16x16x32_bf16 v[58:61], v[162:165], v[202:205], v[58:61]
	v_mfma_f32_16x16x32_bf16 v[46:49], v[154:157], v[210:213], v[46:49]
	v_mfma_f32_16x16x32_bf16 v[42:45], v[162:165], v[210:213], v[42:45]
	v_mfma_f32_16x16x32_bf16 v[30:33], v[154:157], v[218:221], v[30:33]
	v_mfma_f32_16x16x32_bf16 v[26:29], v[162:165], v[218:221], v[26:29]
	v_mfma_f32_16x16x32_bf16 v[14:17], v[154:157], v[226:229], v[14:17]
	v_mfma_f32_16x16x32_bf16 v[10:13], v[162:165], v[226:229], v[10:13]
	v_mfma_f32_16x16x32_bf16 v[62:65], v[158:161], v[206:209], v[62:65]
	v_mfma_f32_16x16x32_bf16 v[58:61], v[166:169], v[206:209], v[58:61]
	v_mfma_f32_16x16x32_bf16 v[46:49], v[158:161], v[214:217], v[46:49]
	v_mfma_f32_16x16x32_bf16 v[42:45], v[166:169], v[214:217], v[42:45]
	v_mfma_f32_16x16x32_bf16 v[30:33], v[158:161], v[222:225], v[30:33]
	v_mfma_f32_16x16x32_bf16 v[26:29], v[166:169], v[222:225], v[26:29]
	v_mfma_f32_16x16x32_bf16 v[14:17], v[158:161], v[230:233], v[14:17]
	v_mfma_f32_16x16x32_bf16 v[10:13], v[166:169], v[230:233], v[10:13]
	s_setprio 0
	s_setprio 1
	v_mfma_f32_16x16x32_bf16 v[54:57], v[170:173], v[202:205], v[54:57]
	v_mfma_f32_16x16x32_bf16 v[50:53], v[182:185], v[202:205], v[50:53]
	v_mfma_f32_16x16x32_bf16 v[38:41], v[170:173], v[210:213], v[38:41]
	v_mfma_f32_16x16x32_bf16 v[34:37], v[182:185], v[210:213], v[34:37]
	v_mfma_f32_16x16x32_bf16 v[22:25], v[170:173], v[218:221], v[22:25]
	v_mfma_f32_16x16x32_bf16 v[18:21], v[182:185], v[218:221], v[18:21]
	v_mfma_f32_16x16x32_bf16 v[6:9], v[170:173], v[226:229], v[6:9]
	v_mfma_f32_16x16x32_bf16 v[2:5], v[182:185], v[226:229], v[2:5]
	v_mfma_f32_16x16x32_bf16 v[54:57], v[174:177], v[206:209], v[54:57]
	v_mfma_f32_16x16x32_bf16 v[50:53], v[198:201], v[206:209], v[50:53]
	v_mfma_f32_16x16x32_bf16 v[38:41], v[174:177], v[214:217], v[38:41]
	v_mfma_f32_16x16x32_bf16 v[34:37], v[198:201], v[214:217], v[34:37]
	v_mfma_f32_16x16x32_bf16 v[22:25], v[174:177], v[222:225], v[22:25]
	v_mfma_f32_16x16x32_bf16 v[18:21], v[198:201], v[222:225], v[18:21]
	v_mfma_f32_16x16x32_bf16 v[6:9], v[174:177], v[230:233], v[6:9]
	v_mfma_f32_16x16x32_bf16 v[2:5], v[198:201], v[230:233], v[2:5]
	s_setprio 0
	s_add_u32 s30, s30, 0x100
	s_addc_u32 s31, s31, 0
	s_add_u32 s14, s14, 0x100
	s_addc_u32 s15, s15, 0
	s_cmp_ge_u32 s21, s80
	s_mov_b32 s20, s21
	s_barrier
	s_cbranch_scc0 .LBB0_224
	s_and_b64 vcc, exec, s[16:17]
	s_cbranch_vccz .LBB0_227
	s_barrier

; #define PG8_STAGE(bufoff, gbase, voff) do { _Pragma("unroll") for (int _i = 0; _i < 2; ++_i) \
;         __builtin_amdgcn_global_load_lds((const unsigned*)((const char*)(gbase) + (voff)[_i]), (PG8_LAS unsigned*)(lds + (bufoff) + ldsw + _i * 8192), 16, 0, 0); } while (0)
; #define PG8_LDA(dst, b, h) do { _Pragma("unroll") for (int m = 0; m < 4; ++m) _Pragma("unroll") for (int k = 0; k < 2; ++k) dst[m][k] = *(const PG8_LAS bf16x8*)(lds + PG8_SA(b, h) + aoff + m * 2048 + k * 1024); } while (0)
; #define PG8_LDB(dst, b, h) do { _Pragma("unroll") for (int n = 0; n < 2; ++n) _Pragma("unroll") for (int k = 0; k < 2; ++k) dst[n][k] = *(const PG8_LAS bf16x8*)(lds + PG8_SB(b, h) + boff + n * 2048 + k * 1024); } while (0)
; #define PG8_MMA(ai, bj, At, Bt) do { __builtin_amdgcn_s_setprio(1); _Pragma("unroll") for (int m = 0; m < 4; ++m) _Pragma("unroll") for (int n = 0; n < 2; ++n) _Pragma("unroll") for (int k = 0; k < 2; ++k) \
;         acc[ai][bj][m][n] = __builtin_amdgcn_mfma_f32_16x16x32_bf16(Bt[n][k], At[m][k], acc[ai][bj][m][n], 0, 0, 0); __builtin_amdgcn_s_setprio(0); } while (0)
; #define PG8_WAIT_V(n) asm volatile("s_waitcnt vmcnt(" #n ")" ::: "memory")
; #define PG8_WAIT_L(n) asm volatile("s_waitcnt lgkmcnt(" #n ")" ::: "memory")
; #define PG8_BAR __builtin_amdgcn_s_barrier()
; #define PG8_SCHED __builtin_amdgcn_sched_barrier(0)
; template <class Epi, class Sched, bool ALIGN_EPI = false, bool SP2 = false>
; __device__ __forceinline__ void gemm_phase(PG8_LAS unsigned char* lds, const Gemm g, const Sched S, const Epi E) {
;     ...
;             const bool last = (t == nt - 2);
;             const char* a1 = cA + (size_t)(t + 1) * kstep;
;             const char* a2 = last ? nA : cA + (size_t)(t + 2) * kstep; const char* b2 = last ? nB : cB + (size_t)(t + 2) * kstep;
;             const char* a3 = a2 + kstep; const char* b3 = b2 + kstep;
;             if (last && has_next) S.a_ready(nxt);
;             if constexpr (SP2) {
;             PG8_LDB(B0, 0, 0); PG8_LDB(B1, 0, 1); PG8_SCHED; PG8_LDA(At, 0, 0); PG8_STAGE(PG8_SA(1, 1), a1 + hstep, voffA);
;             PG8_WAIT_V(8); PG8_WAIT_L(0); PG8_BAR; PG8_MMA(0, 0, At, B0); PG8_MMA(0, 1, At, B1); PG8_BAR; PG8_SCHED;
;             PG8_LDA(At, 0, 1); PG8_STAGE(PG8_SB(0, 0), b2, voffB); PG8_STAGE(PG8_SB(0, 1), b2 + hstep, voffB); PG8_STAGE(PG8_SA(0, 0), a2, voffA);
.LBB0_416:
	v_add_u32_e32 v158, 0x10000, v168
	v_add_u32_e32 v171, 0x14000, v168
	ds_read_b128 v[134:137], v158
	ds_read_b128 v[138:141], v158 offset:1024
	ds_read_b128 v[142:145], v158 offset:2048
	ds_read_b128 v[158:161], v158 offset:3072
	ds_read_b128 v[162:165], v171
	ds_read_b128 v[172:175], v171 offset:1024
	ds_read_b128 v[182:185], v171 offset:2048
	ds_read_b128 v[198:201], v171 offset:3072
	ds_read_b128 v[202:205], v170
	ds_read_b128 v[206:209], v170 offset:1024
	ds_read_b128 v[210:213], v170 offset:2048
	ds_read_b128 v[214:217], v170 offset:3072
	ds_read_b128 v[218:221], v170 offset:4096
	ds_read_b128 v[222:225], v170 offset:5120
	ds_read_b128 v[226:229], v170 offset:6144
	ds_read_b128 v[230:233], v170 offset:7168
	s_add_i32 s3, s14, 2
	s_add_u32 s15, s68, s16
	s_addc_u32 s18, s69, s17
	s_add_u32 s20, s66, s16
	s_addc_u32 s21, s67, s17
	s_add_i32 s22, 0, 0x10000
	s_cmp_eq_u32 s89, s14
	s_cselect_b32 s19, s1, s18
	s_cselect_b32 s18, s0, s15
	s_cselect_b32 s15, s71, s21
	s_cselect_b32 s14, s70, s20
	s_add_i32 s20, 0, 0x14000
	v_lshl_add_u64 v[176:177], s[68:69], 0, v[132:133]
	s_add_i32 m0, s80, 0xc000
	s_nop 0
	global_load_lds_dwordx4 v[176:177], off
	v_lshl_add_u64 v[176:177], s[68:69], 0, v[130:131]
	s_add_i32 m0, s80, 0xe000
	s_nop 0
	global_load_lds_dwordx4 v[176:177], off
	s_waitcnt vmcnt(8)
	s_waitcnt lgkmcnt(0)
	s_barrier
	s_setprio 1
	s_waitcnt lgkmcnt(0)
	v_mfma_f32_16x16x32_bf16 v[58:61], v[134:137], v[202:205], v[58:61]
	v_mfma_f32_16x16x32_bf16 v[50:53], v[142:145], v[202:205], v[50:53]
	v_mfma_f32_16x16x32_bf16 v[14:17], v[134:137], v[210:213], v[14:17]
	v_mfma_f32_16x16x32_bf16 v[10:13], v[142:145], v[210:213], v[10:13]
	v_mfma_f32_16x16x32_bf16 v[30:33], v[134:137], v[218:221], v[30:33]
	v_mfma_f32_16x16x32_bf16 v[26:29], v[142:145], v[218:221], v[26:29]
	v_mfma_f32_16x16x32_bf16 v[46:49], v[134:137], v[226:229], v[46:49]
	v_mfma_f32_16x16x32_bf16 v[42:45], v[142:145], v[226:229], v[42:45]
	v_mfma_f32_16x16x32_bf16 v[58:61], v[138:141], v[206:209], v[58:61]
	v_mfma_f32_16x16x32_bf16 v[50:53], v[158:161], v[206:209], v[50:53]
	v_mfma_f32_16x16x32_bf16 v[14:17], v[138:141], v[214:217], v[14:17]
	v_mfma_f32_16x16x32_bf16 v[10:13], v[158:161], v[214:217], v[10:13]
	v_mfma_f32_16x16x32_bf16 v[30:33], v[138:141], v[222:225], v[30:33]
	v_mfma_f32_16x16x32_bf16 v[26:29], v[158:161], v[222:225], v[26:29]
	v_mfma_f32_16x16x32_bf16 v[46:49], v[138:141], v[230:233], v[46:49]
	v_mfma_f32_16x16x32_bf16 v[42:45], v[158:161], v[230:233], v[42:45]
	s_setprio 0
	s_setprio 1
	v_mfma_f32_16x16x32_bf16 v[6:9], v[162:165], v[202:205], v[6:9]
	v_mfma_f32_16x16x32_bf16 v[2:5], v[182:185], v[202:205], v[2:5]
	v_mfma_f32_16x16x32_bf16 v[22:25], v[162:165], v[210:213], v[22:25]
	v_mfma_f32_16x16x32_bf16 v[18:21], v[182:185], v[210:213], v[18:21]
	v_mfma_f32_16x16x32_bf16 v[38:41], v[162:165], v[218:221], v[38:41]
	v_mfma_f32_16x16x32_bf16 v[34:37], v[182:185], v[218:221], v[34:37]
	v_mfma_f32_16x16x32_bf16 v[62:65], v[162:165], v[226:229], v[62:65]
	v_mfma_f32_16x16x32_bf16 v[54:57], v[182:185], v[226:229], v[54:57]
	v_mfma_f32_16x16x32_bf16 v[6:9], v[172:175], v[206:209], v[6:9]
	v_mfma_f32_16x16x32_bf16 v[2:5], v[198:201], v[206:209], v[2:5]
	v_mfma_f32_16x16x32_bf16 v[22:25], v[172:175], v[214:217], v[22:25]
	v_mfma_f32_16x16x32_bf16 v[18:21], v[198:201], v[214:217], v[18:21]
	v_mfma_f32_16x16x32_bf16 v[38:41], v[172:175], v[222:225], v[38:41]
	v_mfma_f32_16x16x32_bf16 v[34:37], v[198:201], v[222:225], v[34:37]
	v_mfma_f32_16x16x32_bf16 v[62:65], v[172:175], v[230:233], v[62:65]
	v_mfma_f32_16x16x32_bf16 v[54:57], v[198:201], v[230:233], v[54:57]
	s_setprio 0
	s_barrier
	ds_read_b128 v[202:205], v170 offset:16384
	ds_read_b128 v[206:209], v170 offset:17408
	ds_read_b128 v[210:213], v170 offset:18432
	ds_read_b128 v[214:217], v170 offset:19456
	ds_read_b128 v[218:221], v170 offset:20480
	ds_read_b128 v[222:225], v170 offset:21504
	ds_read_b128 v[226:229], v170 offset:22528
	ds_read_b128 v[230:233], v170 offset:23552
	s_add_i32 s21, s22, s79
	v_lshl_add_u64 v[176:177], s[14:15], 0, v[148:149]
	s_mov_b32 m0, s21
	s_nop 0
	global_load_lds_dwordx4 v[176:177], off
	s_add_i32 m0, s21, 0x2000
	v_lshl_add_u64 v[234:235], s[14:15], 0, v[152:153]
	s_add_u32 s14, s14, s28
	s_addc_u32 s15, s15, 0
	s_add_i32 s20, s20, s79
	global_load_lds_dwordx4 v[234:235], off
	v_lshl_add_u64 v[236:237], s[14:15], 0, v[148:149]
	s_mov_b32 m0, s20
	v_lshl_add_u64 v[238:239], s[14:15], 0, v[152:153]
	global_load_lds_dwordx4 v[236:237], off
	s_add_i32 m0, s20, 0x2000
	v_lshl_add_u64 v[240:241], s[18:19], 0, v[146:147]
	global_load_lds_dwordx4 v[238:239], off
	s_mov_b32 m0, s80
	v_lshl_add_u64 v[242:243], s[18:19], 0, v[150:151]
	global_load_lds_dwordx4 v[240:241], off
	s_mov_b32 m0, s81
	s_nop 0
	global_load_lds_dwordx4 v[242:243], off
	s_waitcnt vmcnt(8)
	s_waitcnt lgkmcnt(0)
	s_barrier
; #define PG8_STAGE(bufoff, gbase, voff) do { _Pragma("unroll") for (int _i = 0; _i < 2; ++_i) \
;         __builtin_amdgcn_global_load_lds((const unsigned*)((const char*)(gbase) + (voff)[_i]), (PG8_LAS unsigned*)(lds + (bufoff) + ldsw + _i * 8192), 16, 0, 0); } while (0)
; #define PG8_LDA(dst, b, h) do { _Pragma("unroll") for (int m = 0; m < 4; ++m) _Pragma("unroll") for (int k = 0; k < 2; ++k) dst[m][k] = *(const PG8_LAS bf16x8*)(lds + PG8_SA(b, h) + aoff + m * 2048 + k * 1024); } while (0)
; #define PG8_LDB(dst, b, h) do { _Pragma("unroll") for (int n = 0; n < 2; ++n) _Pragma("unroll") for (int k = 0; k < 2; ++k) dst[n][k] = *(const PG8_LAS bf16x8*)(lds + PG8_SB(b, h) + boff + n * 2048 + k * 1024); } while (0)
; #define PG8_MMA(ai, bj, At, Bt) do { __builtin_amdgcn_s_setprio(1); _Pragma("unroll") for (int m = 0; m < 4; ++m) _Pragma("unroll") for (int n = 0; n < 2; ++n) _Pragma("unroll") for (int k = 0; k < 2; ++k) \
;         acc[ai][bj][m][n] = __builtin_amdgcn_mfma_f32_16x16x32_bf16(Bt[n][k], At[m][k], acc[ai][bj][m][n], 0, 0, 0); __builtin_amdgcn_s_setprio(0); } while (0)
; #define PG8_WAIT_V(n) asm volatile("s_waitcnt vmcnt(" #n ")" ::: "memory")
; #define PG8_WAIT_L(n) asm volatile("s_waitcnt lgkmcnt(" #n ")" ::: "memory")
; #define PG8_BAR __builtin_amdgcn_s_barrier()
; #define PG8_SCHED __builtin_amdgcn_sched_barrier(0)
; template <class Epi, class Sched, bool ALIGN_EPI = false, bool SP2 = false>
; __device__ __forceinline__ void gemm_phase(PG8_LAS unsigned char* lds, const Gemm g, const Sched S, const Epi E) {
;     ...
;             PG8_WAIT_V(8); PG8_WAIT_L(0); PG8_BAR; PG8_MMA(1, 0, At, B0); PG8_MMA(1, 1, At, B1); PG8_BAR; PG8_SCHED;
;             PG8_LDB(B0, 1, 0); PG8_LDB(B1, 1, 1); PG8_SCHED; PG8_LDA(At, 1, 0); PG8_STAGE(PG8_SA(0, 1), a2 + hstep, voffA);
;             PG8_WAIT_V(8); PG8_WAIT_L(0); PG8_BAR; PG8_MMA(0, 0, At, B0); PG8_MMA(0, 1, At, B1); PG8_BAR; PG8_SCHED;
	s_setprio 1
	s_waitcnt lgkmcnt(0)
	v_mfma_f32_16x16x32_bf16 v[70:73], v[134:137], v[202:205], v[70:73]
	v_mfma_f32_16x16x32_bf16 v[66:69], v[142:145], v[202:205], v[66:69]
	v_mfma_f32_16x16x32_bf16 v[86:89], v[134:137], v[210:213], v[86:89]
	v_mfma_f32_16x16x32_bf16 v[82:85], v[142:145], v[210:213], v[82:85]
	v_mfma_f32_16x16x32_bf16 v[102:105], v[134:137], v[218:221], v[102:105]
	v_mfma_f32_16x16x32_bf16 v[98:101], v[142:145], v[218:221], v[98:101]
	v_mfma_f32_16x16x32_bf16 v[118:121], v[134:137], v[226:229], v[118:121]
	v_mfma_f32_16x16x32_bf16 v[114:117], v[142:145], v[226:229], v[114:117]
	v_mfma_f32_16x16x32_bf16 v[70:73], v[138:141], v[206:209], v[70:73]
	v_mfma_f32_16x16x32_bf16 v[66:69], v[158:161], v[206:209], v[66:69]
	v_mfma_f32_16x16x32_bf16 v[86:89], v[138:141], v[214:217], v[86:89]
	v_mfma_f32_16x16x32_bf16 v[82:85], v[158:161], v[214:217], v[82:85]
	v_mfma_f32_16x16x32_bf16 v[102:105], v[138:141], v[222:225], v[102:105]
	v_mfma_f32_16x16x32_bf16 v[98:101], v[158:161], v[222:225], v[98:101]
	v_mfma_f32_16x16x32_bf16 v[118:121], v[138:141], v[230:233], v[118:121]
	v_mfma_f32_16x16x32_bf16 v[114:117], v[158:161], v[230:233], v[114:117]
	s_setprio 0
	s_setprio 1
	v_mfma_f32_16x16x32_bf16 v[78:81], v[162:165], v[202:205], v[78:81]
	v_mfma_f32_16x16x32_bf16 v[74:77], v[182:185], v[202:205], v[74:77]
	v_mfma_f32_16x16x32_bf16 v[94:97], v[162:165], v[210:213], v[94:97]
	v_mfma_f32_16x16x32_bf16 v[90:93], v[182:185], v[210:213], v[90:93]
	v_mfma_f32_16x16x32_bf16 v[110:113], v[162:165], v[218:221], v[110:113]
	v_mfma_f32_16x16x32_bf16 v[106:109], v[182:185], v[218:221], v[106:109]
	v_mfma_f32_16x16x32_bf16 v[126:129], v[162:165], v[226:229], v[126:129]
	v_mfma_f32_16x16x32_bf16 v[122:125], v[182:185], v[226:229], v[122:125]
	v_mfma_f32_16x16x32_bf16 v[78:81], v[172:175], v[206:209], v[78:81]
	v_mfma_f32_16x16x32_bf16 v[74:77], v[198:201], v[206:209], v[74:77]
	v_mfma_f32_16x16x32_bf16 v[94:97], v[172:175], v[214:217], v[94:97]
	v_mfma_f32_16x16x32_bf16 v[90:93], v[198:201], v[214:217], v[90:93]
	v_mfma_f32_16x16x32_bf16 v[110:113], v[172:175], v[222:225], v[110:113]
	v_mfma_f32_16x16x32_bf16 v[106:109], v[198:201], v[222:225], v[106:109]
	v_mfma_f32_16x16x32_bf16 v[126:129], v[172:175], v[230:233], v[126:129]
	v_mfma_f32_16x16x32_bf16 v[122:125], v[198:201], v[230:233], v[122:125]
	s_setprio 0
	s_barrier
	v_add_u32_e32 v158, 0x18000, v168
	v_add_u32_e32 v171, 0x1c000, v168
	ds_read_b128 v[134:137], v158
	ds_read_b128 v[138:141], v158 offset:1024
	ds_read_b128 v[142:145], v158 offset:2048
	ds_read_b128 v[158:161], v158 offset:3072
	ds_read_b128 v[162:165], v171
	ds_read_b128 v[172:175], v171 offset:1024
	ds_read_b128 v[182:185], v171 offset:2048
	ds_read_b128 v[198:201], v171 offset:3072
	ds_read_b128 v[202:205], v170 offset:32768
	ds_read_b128 v[206:209], v170 offset:33792
	ds_read_b128 v[210:213], v170 offset:34816
	ds_read_b128 v[214:217], v170 offset:35840
	ds_read_b128 v[218:221], v170 offset:36864
	ds_read_b128 v[222:225], v170 offset:37888
	ds_read_b128 v[226:229], v170 offset:38912
	ds_read_b128 v[230:233], v170 offset:39936
	s_add_i32 s20, 0, 0x18000
	s_add_i32 s21, 0, 0x1c000
	s_add_u32 s14, s18, s28
	s_addc_u32 s15, s19, 0
	s_mov_b32 m0, s82
	v_lshl_add_u64 v[244:245], s[14:15], 0, v[146:147]
	global_load_lds_dwordx4 v[244:245], off
	v_lshl_add_u64 v[244:245], s[14:15], 0, v[150:151]
	s_mov_b32 m0, s83
	s_nop 0
	global_load_lds_dwordx4 v[244:245], off
	s_waitcnt vmcnt(8)
	s_waitcnt lgkmcnt(0)
	s_barrier
	s_setprio 1
	s_waitcnt lgkmcnt(0)
	v_mfma_f32_16x16x32_bf16 v[58:61], v[134:137], v[202:205], v[58:61]
	v_mfma_f32_16x16x32_bf16 v[50:53], v[142:145], v[202:205], v[50:53]
	v_mfma_f32_16x16x32_bf16 v[14:17], v[134:137], v[210:213], v[14:17]
	v_mfma_f32_16x16x32_bf16 v[10:13], v[142:145], v[210:213], v[10:13]
	v_mfma_f32_16x16x32_bf16 v[30:33], v[134:137], v[218:221], v[30:33]
	v_mfma_f32_16x16x32_bf16 v[26:29], v[142:145], v[218:221], v[26:29]
	v_mfma_f32_16x16x32_bf16 v[46:49], v[134:137], v[226:229], v[46:49]
	v_mfma_f32_16x16x32_bf16 v[42:45], v[142:145], v[226:229], v[42:45]
	v_mfma_f32_16x16x32_bf16 v[58:61], v[138:141], v[206:209], v[58:61]
	v_mfma_f32_16x16x32_bf16 v[50:53], v[158:161], v[206:209], v[50:53]
	v_mfma_f32_16x16x32_bf16 v[14:17], v[138:141], v[214:217], v[14:17]
	v_mfma_f32_16x16x32_bf16 v[10:13], v[158:161], v[214:217], v[10:13]
	v_mfma_f32_16x16x32_bf16 v[30:33], v[138:141], v[222:225], v[30:33]
	v_mfma_f32_16x16x32_bf16 v[26:29], v[158:161], v[222:225], v[26:29]
	v_mfma_f32_16x16x32_bf16 v[46:49], v[138:141], v[230:233], v[46:49]
	v_mfma_f32_16x16x32_bf16 v[42:45], v[158:161], v[230:233], v[42:45]
	s_setprio 0
	s_setprio 1
	v_mfma_f32_16x16x32_bf16 v[6:9], v[162:165], v[202:205], v[6:9]
	v_mfma_f32_16x16x32_bf16 v[2:5], v[182:185], v[202:205], v[2:5]
	v_mfma_f32_16x16x32_bf16 v[22:25], v[162:165], v[210:213], v[22:25]
	v_mfma_f32_16x16x32_bf16 v[18:21], v[182:185], v[210:213], v[18:21]
	v_mfma_f32_16x16x32_bf16 v[38:41], v[162:165], v[218:221], v[38:41]
	v_mfma_f32_16x16x32_bf16 v[34:37], v[182:185], v[218:221], v[34:37]
	v_mfma_f32_16x16x32_bf16 v[62:65], v[162:165], v[226:229], v[62:65]
	v_mfma_f32_16x16x32_bf16 v[54:57], v[182:185], v[226:229], v[54:57]
	v_mfma_f32_16x16x32_bf16 v[6:9], v[172:175], v[206:209], v[6:9]
	v_mfma_f32_16x16x32_bf16 v[2:5], v[198:201], v[206:209], v[2:5]
	v_mfma_f32_16x16x32_bf16 v[22:25], v[172:175], v[214:217], v[22:25]
	v_mfma_f32_16x16x32_bf16 v[18:21], v[198:201], v[214:217], v[18:21]
	v_mfma_f32_16x16x32_bf16 v[38:41], v[172:175], v[222:225], v[38:41]
	v_mfma_f32_16x16x32_bf16 v[34:37], v[198:201], v[222:225], v[34:37]
	v_mfma_f32_16x16x32_bf16 v[62:65], v[172:175], v[230:233], v[62:65]
	v_mfma_f32_16x16x32_bf16 v[54:57], v[198:201], v[230:233], v[54:57]
	s_setprio 0
	s_barrier
; #define PG8_STAGE(bufoff, gbase, voff) do { _Pragma("unroll") for (int _i = 0; _i < 2; ++_i) \
;         __builtin_amdgcn_global_load_lds((const unsigned*)((const char*)(gbase) + (voff)[_i]), (PG8_LAS unsigned*)(lds + (bufoff) + ldsw + _i * 8192), 16, 0, 0); } while (0)
; #define PG8_LDA(dst, b, h) do { _Pragma("unroll") for (int m = 0; m < 4; ++m) _Pragma("unroll") for (int k = 0; k < 2; ++k) dst[m][k] = *(const PG8_LAS bf16x8*)(lds + PG8_SA(b, h) + aoff + m * 2048 + k * 1024); } while (0)
; #define PG8_MMA(ai, bj, At, Bt) do { __builtin_amdgcn_s_setprio(1); _Pragma("unroll") for (int m = 0; m < 4; ++m) _Pragma("unroll") for (int n = 0; n < 2; ++n) _Pragma("unroll") for (int k = 0; k < 2; ++k) \
;         acc[ai][bj][m][n] = __builtin_amdgcn_mfma_f32_16x16x32_bf16(Bt[n][k], At[m][k], acc[ai][bj][m][n], 0, 0, 0); __builtin_amdgcn_s_setprio(0); } while (0)
; #define PG8_WAIT_V(n) asm volatile("s_waitcnt vmcnt(" #n ")" ::: "memory")
; #define PG8_WAIT_L(n) asm volatile("s_waitcnt lgkmcnt(" #n ")" ::: "memory")
; #define PG8_BAR __builtin_amdgcn_s_barrier()
; #define PG8_SCHED __builtin_amdgcn_sched_barrier(0)
; template <class Epi, class Sched, bool ALIGN_EPI = false, bool SP2 = false>
; __device__ __forceinline__ void gemm_phase(PG8_LAS unsigned char* lds, const Gemm g, const Sched S, const Epi E) {
;     ...
;             PG8_LDA(At, 1, 1); PG8_STAGE(PG8_SB(1, 0), b3, voffB); PG8_STAGE(PG8_SB(1, 1), b3 + hstep, voffB); PG8_STAGE(PG8_SA(1, 0), a3, voffA);
;             PG8_WAIT_V(8); PG8_WAIT_L(0); PG8_BAR; PG8_MMA(1, 0, At, B0); PG8_MMA(1, 1, At, B1); PG8_BAR; PG8_SCHED;
;     ...
;         }
;         if constexpr (ALIGN_EPI) { if (wr == 0) PG8_BAR; }
	ds_read_b128 v[202:205], v170 offset:49152
	ds_read_b128 v[206:209], v170 offset:50176
	ds_read_b128 v[210:213], v170 offset:51200
	ds_read_b128 v[214:217], v170 offset:52224
	ds_read_b128 v[218:221], v170 offset:53248
	ds_read_b128 v[222:225], v170 offset:54272
	ds_read_b128 v[226:229], v170 offset:55296
	ds_read_b128 v[230:233], v170 offset:56320
	s_add_i32 s14, s20, s79
	v_lshl_add_u64 v[176:177], v[176:177], 0, s[12:13]
	s_mov_b32 m0, s14
	s_nop 0
	global_load_lds_dwordx4 v[176:177], off
	v_lshl_add_u64 v[176:177], v[234:235], 0, s[12:13]
	s_add_i32 m0, s14, 0x2000
	s_add_i32 s14, s21, s79
	global_load_lds_dwordx4 v[176:177], off
	v_lshl_add_u64 v[176:177], v[236:237], 0, s[12:13]
	s_mov_b32 m0, s14
	s_nop 0
	global_load_lds_dwordx4 v[176:177], off
	v_lshl_add_u64 v[176:177], v[238:239], 0, s[12:13]
	s_add_i32 m0, s14, 0x2000
	s_nop 0
	global_load_lds_dwordx4 v[176:177], off
	v_lshl_add_u64 v[176:177], v[240:241], 0, s[12:13]
	s_mov_b32 m0, s84
	s_nop 0
	global_load_lds_dwordx4 v[176:177], off
	v_lshl_add_u64 v[176:177], v[242:243], 0, s[12:13]
	s_mov_b32 m0, s85
	s_nop 0
	global_load_lds_dwordx4 v[176:177], off
	s_waitcnt vmcnt(8)
	s_waitcnt lgkmcnt(0)
	s_barrier
	s_setprio 1
	s_waitcnt lgkmcnt(0)
	v_mfma_f32_16x16x32_bf16 v[70:73], v[134:137], v[202:205], v[70:73]
	v_mfma_f32_16x16x32_bf16 v[66:69], v[142:145], v[202:205], v[66:69]
	v_mfma_f32_16x16x32_bf16 v[86:89], v[134:137], v[210:213], v[86:89]
	v_mfma_f32_16x16x32_bf16 v[82:85], v[142:145], v[210:213], v[82:85]
	v_mfma_f32_16x16x32_bf16 v[102:105], v[134:137], v[218:221], v[102:105]
	v_mfma_f32_16x16x32_bf16 v[98:101], v[142:145], v[218:221], v[98:101]
	v_mfma_f32_16x16x32_bf16 v[118:121], v[134:137], v[226:229], v[118:121]
	v_mfma_f32_16x16x32_bf16 v[114:117], v[142:145], v[226:229], v[114:117]
	v_mfma_f32_16x16x32_bf16 v[70:73], v[138:141], v[206:209], v[70:73]
	v_mfma_f32_16x16x32_bf16 v[66:69], v[158:161], v[206:209], v[66:69]
	v_mfma_f32_16x16x32_bf16 v[86:89], v[138:141], v[214:217], v[86:89]
	v_mfma_f32_16x16x32_bf16 v[82:85], v[158:161], v[214:217], v[82:85]
	v_mfma_f32_16x16x32_bf16 v[102:105], v[138:141], v[222:225], v[102:105]
	v_mfma_f32_16x16x32_bf16 v[98:101], v[158:161], v[222:225], v[98:101]
	v_mfma_f32_16x16x32_bf16 v[118:121], v[138:141], v[230:233], v[118:121]
	v_mfma_f32_16x16x32_bf16 v[114:117], v[158:161], v[230:233], v[114:117]
	s_setprio 0
	s_setprio 1
	v_mfma_f32_16x16x32_bf16 v[78:81], v[162:165], v[202:205], v[78:81]
	v_mfma_f32_16x16x32_bf16 v[74:77], v[182:185], v[202:205], v[74:77]
	v_mfma_f32_16x16x32_bf16 v[94:97], v[162:165], v[210:213], v[94:97]
	v_mfma_f32_16x16x32_bf16 v[90:93], v[182:185], v[210:213], v[90:93]
	v_mfma_f32_16x16x32_bf16 v[110:113], v[162:165], v[218:221], v[110:113]
	v_mfma_f32_16x16x32_bf16 v[106:109], v[182:185], v[218:221], v[106:109]
	v_mfma_f32_16x16x32_bf16 v[126:129], v[162:165], v[226:229], v[126:129]
	v_mfma_f32_16x16x32_bf16 v[122:125], v[182:185], v[226:229], v[122:125]
	v_mfma_f32_16x16x32_bf16 v[78:81], v[172:175], v[206:209], v[78:81]
	v_mfma_f32_16x16x32_bf16 v[74:77], v[198:201], v[206:209], v[74:77]
	v_mfma_f32_16x16x32_bf16 v[94:97], v[172:175], v[214:217], v[94:97]
	v_mfma_f32_16x16x32_bf16 v[90:93], v[198:201], v[214:217], v[90:93]
	v_mfma_f32_16x16x32_bf16 v[110:113], v[172:175], v[222:225], v[110:113]
	v_mfma_f32_16x16x32_bf16 v[106:109], v[198:201], v[222:225], v[106:109]
	v_mfma_f32_16x16x32_bf16 v[126:129], v[172:175], v[230:233], v[126:129]
	v_mfma_f32_16x16x32_bf16 v[122:125], v[198:201], v[230:233], v[122:125]
	s_setprio 0
	s_add_u32 s16, s16, 0x100
	s_addc_u32 s17, s17, 0
	v_lshl_add_u64 v[132:133], v[132:133], 0, s[30:31]
	v_lshl_add_u64 v[130:131], v[130:131], 0, s[30:31]
	s_cmp_ge_u32 s3, s88
	s_mov_b32 s14, s3
	s_barrier
	s_cbranch_scc0 .LBB0_416
	s_and_b64 vcc, exec, s[62:63]
	s_cbranch_vccz .LBB0_419
	s_barrier

; #define PG8_STAGE(bufoff, gbase, voff) do { _Pragma("unroll") for (int _i = 0; _i < 2; ++_i) \
;         __builtin_amdgcn_global_load_lds((const unsigned*)((const char*)(gbase) + (voff)[_i]), (PG8_LAS unsigned*)(lds + (bufoff) + ldsw + _i * 8192), 16, 0, 0); } while (0)
; #define PG8_LDA(dst, b, h) do { _Pragma("unroll") for (int m = 0; m < 4; ++m) _Pragma("unroll") for (int k = 0; k < 2; ++k) dst[m][k] = *(const PG8_LAS bf16x8*)(lds + PG8_SA(b, h) + aoff + m * 2048 + k * 1024); } while (0)
; #define PG8_LDB(dst, b, h) do { _Pragma("unroll") for (int n = 0; n < 2; ++n) _Pragma("unroll") for (int k = 0; k < 2; ++k) dst[n][k] = *(const PG8_LAS bf16x8*)(lds + PG8_SB(b, h) + boff + n * 2048 + k * 1024); } while (0)
; #define PG8_MMA(ai, bj, At, Bt) do { __builtin_amdgcn_s_setprio(1); _Pragma("unroll") for (int m = 0; m < 4; ++m) _Pragma("unroll") for (int n = 0; n < 2; ++n) _Pragma("unroll") for (int k = 0; k < 2; ++k) \
;         acc[ai][bj][m][n] = __builtin_amdgcn_mfma_f32_16x16x32_bf16(Bt[n][k], At[m][k], acc[ai][bj][m][n], 0, 0, 0); __builtin_amdgcn_s_setprio(0); } while (0)
; #define PG8_WAIT_V(n) asm volatile("s_waitcnt vmcnt(" #n ")" ::: "memory")
; #define PG8_WAIT_L(n) asm volatile("s_waitcnt lgkmcnt(" #n ")" ::: "memory")
; #define PG8_BAR __builtin_amdgcn_s_barrier()
; #define PG8_SCHED __builtin_amdgcn_sched_barrier(0)
; template <class Epi, class Sched, bool ALIGN_EPI = false, bool SP2 = false>
; __device__ __forceinline__ void gemm_phase(PG8_LAS unsigned char* lds, const Gemm g, const Sched S, const Epi E) {
;     ...
;             const bool last = (t == nt - 2);
;             const char* a1 = cA + (size_t)(t + 1) * kstep;
;             const char* a2 = last ? nA : cA + (size_t)(t + 2) * kstep; const char* b2 = last ? nB : cB + (size_t)(t + 2) * kstep;
;             const char* a3 = a2 + kstep; const char* b3 = b2 + kstep;
;             if (last && has_next) S.a_ready(nxt);
;             if constexpr (SP2) {
;             PG8_LDB(B0, 0, 0); PG8_LDB(B1, 0, 1); PG8_SCHED; PG8_LDA(At, 0, 0); PG8_STAGE(PG8_SA(1, 1), a1 + hstep, voffA);
;             PG8_WAIT_V(8); PG8_WAIT_L(0); PG8_BAR; PG8_MMA(0, 0, At, B0); PG8_MMA(0, 1, At, B1); PG8_BAR; PG8_SCHED;
;             PG8_LDA(At, 0, 1); PG8_STAGE(PG8_SB(0, 0), b2, voffB); PG8_STAGE(PG8_SB(0, 1), b2 + hstep, voffB); PG8_STAGE(PG8_SA(0, 0), a2, voffA);
.LBB0_538:
	v_add_u32_e32 v155, 0x10000, v152
	ds_read_b128 v[146:149], v155
	ds_read_b128 v[156:159], v155 offset:1024
	ds_read_b128 v[160:163], v155 offset:2048
	ds_read_b128 v[164:167], v155 offset:3072
	v_add_u32_e32 v155, 0x14000, v152
	ds_read_b128 v[168:171], v155
	ds_read_b128 v[172:175], v155 offset:1024
	ds_read_b128 v[182:185], v155 offset:2048
	ds_read_b128 v[198:201], v155 offset:3072
	ds_read_b128 v[202:205], v154
	ds_read_b128 v[206:209], v154 offset:1024
	ds_read_b128 v[210:213], v154 offset:2048
	ds_read_b128 v[214:217], v154 offset:3072
	ds_read_b128 v[218:221], v154 offset:4096
	ds_read_b128 v[222:225], v154 offset:5120
	ds_read_b128 v[226:229], v154 offset:6144
	ds_read_b128 v[230:233], v154 offset:7168
	s_add_i32 s3, s14, 2
	s_add_u32 s15, s68, s16
	s_addc_u32 s18, s69, s17
	s_add_u32 s20, s66, s16
	s_addc_u32 s21, s67, s17
	s_add_i32 s22, 0, 0x10000
	s_cmp_eq_u32 s81, s14
	s_cselect_b32 s19, s1, s18
	s_cselect_b32 s18, s0, s15
	s_cselect_b32 s15, s55, s21
	s_cselect_b32 s14, s54, s20
	s_add_i32 s20, 0, 0x14000
	v_lshl_add_u64 v[176:177], s[68:69], 0, v[144:145]
	s_add_i32 m0, s72, 0xc000
	s_nop 0
	global_load_lds_dwordx4 v[176:177], off
	v_lshl_add_u64 v[176:177], s[68:69], 0, v[142:143]
	s_add_i32 m0, s72, 0xe000
	s_nop 0
	global_load_lds_dwordx4 v[176:177], off
	s_waitcnt vmcnt(8)
	s_waitcnt lgkmcnt(0)
	s_barrier
	s_setprio 1
	s_waitcnt lgkmcnt(0)
	v_mfma_f32_16x16x32_bf16 v[62:65], v[146:149], v[202:205], v[62:65]
	v_mfma_f32_16x16x32_bf16 v[54:57], v[160:163], v[202:205], v[54:57]
	v_mfma_f32_16x16x32_bf16 v[14:17], v[146:149], v[210:213], v[14:17]
	v_mfma_f32_16x16x32_bf16 v[10:13], v[160:163], v[210:213], v[10:13]
	v_mfma_f32_16x16x32_bf16 v[30:33], v[146:149], v[218:221], v[30:33]
	v_mfma_f32_16x16x32_bf16 v[26:29], v[160:163], v[218:221], v[26:29]
	v_mfma_f32_16x16x32_bf16 v[46:49], v[146:149], v[226:229], v[46:49]
	v_mfma_f32_16x16x32_bf16 v[42:45], v[160:163], v[226:229], v[42:45]
	v_mfma_f32_16x16x32_bf16 v[62:65], v[156:159], v[206:209], v[62:65]
	v_mfma_f32_16x16x32_bf16 v[54:57], v[164:167], v[206:209], v[54:57]
	v_mfma_f32_16x16x32_bf16 v[14:17], v[156:159], v[214:217], v[14:17]
	v_mfma_f32_16x16x32_bf16 v[10:13], v[164:167], v[214:217], v[10:13]
	v_mfma_f32_16x16x32_bf16 v[30:33], v[156:159], v[222:225], v[30:33]
	v_mfma_f32_16x16x32_bf16 v[26:29], v[164:167], v[222:225], v[26:29]
	v_mfma_f32_16x16x32_bf16 v[46:49], v[156:159], v[230:233], v[46:49]
	v_mfma_f32_16x16x32_bf16 v[42:45], v[164:167], v[230:233], v[42:45]
	s_setprio 0
	s_setprio 1
	v_mfma_f32_16x16x32_bf16 v[6:9], v[168:171], v[202:205], v[6:9]
	v_mfma_f32_16x16x32_bf16 v[2:5], v[182:185], v[202:205], v[2:5]
	v_mfma_f32_16x16x32_bf16 v[22:25], v[168:171], v[210:213], v[22:25]
	v_mfma_f32_16x16x32_bf16 v[18:21], v[182:185], v[210:213], v[18:21]
	v_mfma_f32_16x16x32_bf16 v[38:41], v[168:171], v[218:221], v[38:41]
	v_mfma_f32_16x16x32_bf16 v[34:37], v[182:185], v[218:221], v[34:37]
	v_mfma_f32_16x16x32_bf16 v[58:61], v[168:171], v[226:229], v[58:61]
	v_mfma_f32_16x16x32_bf16 v[50:53], v[182:185], v[226:229], v[50:53]
	v_mfma_f32_16x16x32_bf16 v[6:9], v[172:175], v[206:209], v[6:9]
	v_mfma_f32_16x16x32_bf16 v[2:5], v[198:201], v[206:209], v[2:5]
	v_mfma_f32_16x16x32_bf16 v[22:25], v[172:175], v[214:217], v[22:25]
	v_mfma_f32_16x16x32_bf16 v[18:21], v[198:201], v[214:217], v[18:21]
	v_mfma_f32_16x16x32_bf16 v[38:41], v[172:175], v[222:225], v[38:41]
	v_mfma_f32_16x16x32_bf16 v[34:37], v[198:201], v[222:225], v[34:37]
	v_mfma_f32_16x16x32_bf16 v[58:61], v[172:175], v[230:233], v[58:61]
	v_mfma_f32_16x16x32_bf16 v[50:53], v[198:201], v[230:233], v[50:53]
	s_setprio 0
	s_barrier
	ds_read_b128 v[202:205], v154 offset:16384
	ds_read_b128 v[206:209], v154 offset:17408
	ds_read_b128 v[210:213], v154 offset:18432
	ds_read_b128 v[214:217], v154 offset:19456
	ds_read_b128 v[218:221], v154 offset:20480
	ds_read_b128 v[222:225], v154 offset:21504
	ds_read_b128 v[226:229], v154 offset:22528
	ds_read_b128 v[230:233], v154 offset:23552
	s_add_i32 s21, s22, s71
	v_lshl_add_u64 v[176:177], s[14:15], 0, v[0:1]
	s_mov_b32 m0, s21
	s_nop 0
	global_load_lds_dwordx4 v[176:177], off
	s_add_i32 m0, s21, 0x2000
	v_lshl_add_u64 v[234:235], s[14:15], 0, v[134:135]
	s_add_u32 s14, s14, s28
	s_addc_u32 s15, s15, 0
	s_add_i32 s20, s20, s71
	global_load_lds_dwordx4 v[234:235], off
	v_lshl_add_u64 v[236:237], s[14:15], 0, v[0:1]
	s_mov_b32 m0, s20
	v_lshl_add_u64 v[238:239], s[14:15], 0, v[134:135]
	global_load_lds_dwordx4 v[236:237], off
	s_add_i32 m0, s20, 0x2000
	v_lshl_add_u64 v[240:241], s[18:19], 0, v[130:131]
	global_load_lds_dwordx4 v[238:239], off
	s_mov_b32 m0, s72
	v_lshl_add_u64 v[242:243], s[18:19], 0, v[132:133]
	global_load_lds_dwordx4 v[240:241], off
	s_mov_b32 m0, s73
	s_nop 0
	global_load_lds_dwordx4 v[242:243], off
	s_waitcnt vmcnt(8)
	s_waitcnt lgkmcnt(0)
	s_barrier
; #define PG8_STAGE(bufoff, gbase, voff) do { _Pragma("unroll") for (int _i = 0; _i < 2; ++_i) \
;         __builtin_amdgcn_global_load_lds((const unsigned*)((const char*)(gbase) + (voff)[_i]), (PG8_LAS unsigned*)(lds + (bufoff) + ldsw + _i * 8192), 16, 0, 0); } while (0)
; #define PG8_LDA(dst, b, h) do { _Pragma("unroll") for (int m = 0; m < 4; ++m) _Pragma("unroll") for (int k = 0; k < 2; ++k) dst[m][k] = *(const PG8_LAS bf16x8*)(lds + PG8_SA(b, h) + aoff + m * 2048 + k * 1024); } while (0)
; #define PG8_LDB(dst, b, h) do { _Pragma("unroll") for (int n = 0; n < 2; ++n) _Pragma("unroll") for (int k = 0; k < 2; ++k) dst[n][k] = *(const PG8_LAS bf16x8*)(lds + PG8_SB(b, h) + boff + n * 2048 + k * 1024); } while (0)
; #define PG8_MMA(ai, bj, At, Bt) do { __builtin_amdgcn_s_setprio(1); _Pragma("unroll") for (int m = 0; m < 4; ++m) _Pragma("unroll") for (int n = 0; n < 2; ++n) _Pragma("unroll") for (int k = 0; k < 2; ++k) \
;         acc[ai][bj][m][n] = __builtin_amdgcn_mfma_f32_16x16x32_bf16(Bt[n][k], At[m][k], acc[ai][bj][m][n], 0, 0, 0); __builtin_amdgcn_s_setprio(0); } while (0)
; #define PG8_WAIT_V(n) asm volatile("s_waitcnt vmcnt(" #n ")" ::: "memory")
; #define PG8_WAIT_L(n) asm volatile("s_waitcnt lgkmcnt(" #n ")" ::: "memory")
; #define PG8_BAR __builtin_amdgcn_s_barrier()
; #define PG8_SCHED __builtin_amdgcn_sched_barrier(0)
; template <class Epi, class Sched, bool ALIGN_EPI = false, bool SP2 = false>
; __device__ __forceinline__ void gemm_phase(PG8_LAS unsigned char* lds, const Gemm g, const Sched S, const Epi E) {
;     ...
;             PG8_WAIT_V(8); PG8_WAIT_L(0); PG8_BAR; PG8_MMA(1, 0, At, B0); PG8_MMA(1, 1, At, B1); PG8_BAR; PG8_SCHED;
;             PG8_LDB(B0, 1, 0); PG8_LDB(B1, 1, 1); PG8_SCHED; PG8_LDA(At, 1, 0); PG8_STAGE(PG8_SA(0, 1), a2 + hstep, voffA);
;             PG8_WAIT_V(8); PG8_WAIT_L(0); PG8_BAR; PG8_MMA(0, 0, At, B0); PG8_MMA(0, 1, At, B1); PG8_BAR; PG8_SCHED;
	s_setprio 1
	s_waitcnt lgkmcnt(0)
	v_mfma_f32_16x16x32_bf16 v[70:73], v[146:149], v[202:205], v[70:73]
	v_mfma_f32_16x16x32_bf16 v[66:69], v[160:163], v[202:205], v[66:69]
	v_mfma_f32_16x16x32_bf16 v[86:89], v[146:149], v[210:213], v[86:89]
	v_mfma_f32_16x16x32_bf16 v[82:85], v[160:163], v[210:213], v[82:85]
	v_mfma_f32_16x16x32_bf16 v[102:105], v[146:149], v[218:221], v[102:105]
	v_mfma_f32_16x16x32_bf16 v[98:101], v[160:163], v[218:221], v[98:101]
	v_mfma_f32_16x16x32_bf16 v[118:121], v[146:149], v[226:229], v[118:121]
	v_mfma_f32_16x16x32_bf16 v[114:117], v[160:163], v[226:229], v[114:117]
	v_mfma_f32_16x16x32_bf16 v[70:73], v[156:159], v[206:209], v[70:73]
	v_mfma_f32_16x16x32_bf16 v[66:69], v[164:167], v[206:209], v[66:69]
	v_mfma_f32_16x16x32_bf16 v[86:89], v[156:159], v[214:217], v[86:89]
	v_mfma_f32_16x16x32_bf16 v[82:85], v[164:167], v[214:217], v[82:85]
	v_mfma_f32_16x16x32_bf16 v[102:105], v[156:159], v[222:225], v[102:105]
	v_mfma_f32_16x16x32_bf16 v[98:101], v[164:167], v[222:225], v[98:101]
	v_mfma_f32_16x16x32_bf16 v[118:121], v[156:159], v[230:233], v[118:121]
	v_mfma_f32_16x16x32_bf16 v[114:117], v[164:167], v[230:233], v[114:117]
	s_setprio 0
	s_setprio 1
	v_mfma_f32_16x16x32_bf16 v[78:81], v[168:171], v[202:205], v[78:81]
	v_mfma_f32_16x16x32_bf16 v[74:77], v[182:185], v[202:205], v[74:77]
	v_mfma_f32_16x16x32_bf16 v[94:97], v[168:171], v[210:213], v[94:97]
	v_mfma_f32_16x16x32_bf16 v[90:93], v[182:185], v[210:213], v[90:93]
	v_mfma_f32_16x16x32_bf16 v[110:113], v[168:171], v[218:221], v[110:113]
	v_mfma_f32_16x16x32_bf16 v[106:109], v[182:185], v[218:221], v[106:109]
	v_mfma_f32_16x16x32_bf16 v[126:129], v[168:171], v[226:229], v[126:129]
	v_mfma_f32_16x16x32_bf16 v[122:125], v[182:185], v[226:229], v[122:125]
	v_mfma_f32_16x16x32_bf16 v[78:81], v[172:175], v[206:209], v[78:81]
	v_mfma_f32_16x16x32_bf16 v[74:77], v[198:201], v[206:209], v[74:77]
	v_mfma_f32_16x16x32_bf16 v[94:97], v[172:175], v[214:217], v[94:97]
	v_mfma_f32_16x16x32_bf16 v[90:93], v[198:201], v[214:217], v[90:93]
	v_mfma_f32_16x16x32_bf16 v[110:113], v[172:175], v[222:225], v[110:113]
	v_mfma_f32_16x16x32_bf16 v[106:109], v[198:201], v[222:225], v[106:109]
	v_mfma_f32_16x16x32_bf16 v[126:129], v[172:175], v[230:233], v[126:129]
	v_mfma_f32_16x16x32_bf16 v[122:125], v[198:201], v[230:233], v[122:125]
	s_setprio 0
	s_barrier
	v_add_u32_e32 v155, 0x18000, v152
	ds_read_b128 v[146:149], v155
	ds_read_b128 v[156:159], v155 offset:1024
	ds_read_b128 v[160:163], v155 offset:2048
	ds_read_b128 v[164:167], v155 offset:3072
	v_add_u32_e32 v155, 0x1c000, v152
	ds_read_b128 v[168:171], v155
	ds_read_b128 v[172:175], v155 offset:1024
	ds_read_b128 v[182:185], v155 offset:2048
	ds_read_b128 v[198:201], v155 offset:3072
	ds_read_b128 v[202:205], v154 offset:32768
	ds_read_b128 v[206:209], v154 offset:33792
	ds_read_b128 v[210:213], v154 offset:34816
	ds_read_b128 v[214:217], v154 offset:35840
	ds_read_b128 v[218:221], v154 offset:36864
	ds_read_b128 v[222:225], v154 offset:37888
	ds_read_b128 v[226:229], v154 offset:38912
	ds_read_b128 v[230:233], v154 offset:39936
	s_add_i32 s20, 0, 0x18000
	s_add_i32 s21, 0, 0x1c000
	s_add_u32 s14, s18, s28
	s_addc_u32 s15, s19, 0
	s_mov_b32 m0, s74
	v_lshl_add_u64 v[244:245], s[14:15], 0, v[130:131]
	global_load_lds_dwordx4 v[244:245], off
	v_lshl_add_u64 v[244:245], s[14:15], 0, v[132:133]
	s_mov_b32 m0, s75
	s_nop 0
	global_load_lds_dwordx4 v[244:245], off
	s_waitcnt vmcnt(8)
	s_waitcnt lgkmcnt(0)
	s_barrier
	s_setprio 1
	s_waitcnt lgkmcnt(0)
	v_mfma_f32_16x16x32_bf16 v[62:65], v[146:149], v[202:205], v[62:65]
	v_mfma_f32_16x16x32_bf16 v[54:57], v[160:163], v[202:205], v[54:57]
	v_mfma_f32_16x16x32_bf16 v[14:17], v[146:149], v[210:213], v[14:17]
	v_mfma_f32_16x16x32_bf16 v[10:13], v[160:163], v[210:213], v[10:13]
	v_mfma_f32_16x16x32_bf16 v[30:33], v[146:149], v[218:221], v[30:33]
	v_mfma_f32_16x16x32_bf16 v[26:29], v[160:163], v[218:221], v[26:29]
	v_mfma_f32_16x16x32_bf16 v[46:49], v[146:149], v[226:229], v[46:49]
	v_mfma_f32_16x16x32_bf16 v[42:45], v[160:163], v[226:229], v[42:45]
	v_mfma_f32_16x16x32_bf16 v[62:65], v[156:159], v[206:209], v[62:65]
	v_mfma_f32_16x16x32_bf16 v[54:57], v[164:167], v[206:209], v[54:57]
	v_mfma_f32_16x16x32_bf16 v[14:17], v[156:159], v[214:217], v[14:17]
	v_mfma_f32_16x16x32_bf16 v[10:13], v[164:167], v[214:217], v[10:13]
	v_mfma_f32_16x16x32_bf16 v[30:33], v[156:159], v[222:225], v[30:33]
	v_mfma_f32_16x16x32_bf16 v[26:29], v[164:167], v[222:225], v[26:29]
	v_mfma_f32_16x16x32_bf16 v[46:49], v[156:159], v[230:233], v[46:49]
	v_mfma_f32_16x16x32_bf16 v[42:45], v[164:167], v[230:233], v[42:45]
	s_setprio 0
	s_setprio 1
	v_mfma_f32_16x16x32_bf16 v[6:9], v[168:171], v[202:205], v[6:9]
	v_mfma_f32_16x16x32_bf16 v[2:5], v[182:185], v[202:205], v[2:5]
	v_mfma_f32_16x16x32_bf16 v[22:25], v[168:171], v[210:213], v[22:25]
	v_mfma_f32_16x16x32_bf16 v[18:21], v[182:185], v[210:213], v[18:21]
	v_mfma_f32_16x16x32_bf16 v[38:41], v[168:171], v[218:221], v[38:41]
	v_mfma_f32_16x16x32_bf16 v[34:37], v[182:185], v[218:221], v[34:37]
	v_mfma_f32_16x16x32_bf16 v[58:61], v[168:171], v[226:229], v[58:61]
	v_mfma_f32_16x16x32_bf16 v[50:53], v[182:185], v[226:229], v[50:53]
	v_mfma_f32_16x16x32_bf16 v[6:9], v[172:175], v[206:209], v[6:9]
	v_mfma_f32_16x16x32_bf16 v[2:5], v[198:201], v[206:209], v[2:5]
	v_mfma_f32_16x16x32_bf16 v[22:25], v[172:175], v[214:217], v[22:25]
	v_mfma_f32_16x16x32_bf16 v[18:21], v[198:201], v[214:217], v[18:21]
	v_mfma_f32_16x16x32_bf16 v[38:41], v[172:175], v[222:225], v[38:41]
	v_mfma_f32_16x16x32_bf16 v[34:37], v[198:201], v[222:225], v[34:37]
	v_mfma_f32_16x16x32_bf16 v[58:61], v[172:175], v[230:233], v[58:61]
	v_mfma_f32_16x16x32_bf16 v[50:53], v[198:201], v[230:233], v[50:53]
	s_setprio 0
	s_barrier
; #define PG8_STAGE(bufoff, gbase, voff) do { _Pragma("unroll") for (int _i = 0; _i < 2; ++_i) \
;         __builtin_amdgcn_global_load_lds((const unsigned*)((const char*)(gbase) + (voff)[_i]), (PG8_LAS unsigned*)(lds + (bufoff) + ldsw + _i * 8192), 16, 0, 0); } while (0)
; #define PG8_LDA(dst, b, h) do { _Pragma("unroll") for (int m = 0; m < 4; ++m) _Pragma("unroll") for (int k = 0; k < 2; ++k) dst[m][k] = *(const PG8_LAS bf16x8*)(lds + PG8_SA(b, h) + aoff + m * 2048 + k * 1024); } while (0)
; #define PG8_MMA(ai, bj, At, Bt) do { __builtin_amdgcn_s_setprio(1); _Pragma("unroll") for (int m = 0; m < 4; ++m) _Pragma("unroll") for (int n = 0; n < 2; ++n) _Pragma("unroll") for (int k = 0; k < 2; ++k) \
;         acc[ai][bj][m][n] = __builtin_amdgcn_mfma_f32_16x16x32_bf16(Bt[n][k], At[m][k], acc[ai][bj][m][n], 0, 0, 0); __builtin_amdgcn_s_setprio(0); } while (0)
; #define PG8_WAIT_V(n) asm volatile("s_waitcnt vmcnt(" #n ")" ::: "memory")
; #define PG8_WAIT_L(n) asm volatile("s_waitcnt lgkmcnt(" #n ")" ::: "memory")
; #define PG8_BAR __builtin_amdgcn_s_barrier()
; #define PG8_SCHED __builtin_amdgcn_sched_barrier(0)
; template <class Epi, class Sched, bool ALIGN_EPI = false, bool SP2 = false>
; __device__ __forceinline__ void gemm_phase(PG8_LAS unsigned char* lds, const Gemm g, const Sched S, const Epi E) {
;     ...
;             PG8_LDA(At, 1, 1); PG8_STAGE(PG8_SB(1, 0), b3, voffB); PG8_STAGE(PG8_SB(1, 1), b3 + hstep, voffB); PG8_STAGE(PG8_SA(1, 0), a3, voffA);
;             PG8_WAIT_V(8); PG8_WAIT_L(0); PG8_BAR; PG8_MMA(1, 0, At, B0); PG8_MMA(1, 1, At, B1); PG8_BAR; PG8_SCHED;
;     ...
;         }
;         if constexpr (ALIGN_EPI) { if (wr == 0) PG8_BAR; }
	ds_read_b128 v[202:205], v154 offset:49152
	ds_read_b128 v[206:209], v154 offset:50176
	ds_read_b128 v[210:213], v154 offset:51200
	ds_read_b128 v[214:217], v154 offset:52224
	ds_read_b128 v[218:221], v154 offset:53248
	ds_read_b128 v[222:225], v154 offset:54272
	ds_read_b128 v[226:229], v154 offset:55296
	ds_read_b128 v[230:233], v154 offset:56320
	s_add_i32 s14, s20, s71
	v_lshl_add_u64 v[176:177], v[176:177], 0, s[12:13]
	s_mov_b32 m0, s14
	s_nop 0
	global_load_lds_dwordx4 v[176:177], off
	v_lshl_add_u64 v[176:177], v[234:235], 0, s[12:13]
	s_add_i32 m0, s14, 0x2000
	s_add_i32 s14, s21, s71
	global_load_lds_dwordx4 v[176:177], off
	v_lshl_add_u64 v[176:177], v[236:237], 0, s[12:13]
	s_mov_b32 m0, s14
	s_nop 0
	global_load_lds_dwordx4 v[176:177], off
	v_lshl_add_u64 v[176:177], v[238:239], 0, s[12:13]
	s_add_i32 m0, s14, 0x2000
	s_nop 0
	global_load_lds_dwordx4 v[176:177], off
	v_lshl_add_u64 v[176:177], v[240:241], 0, s[12:13]
	s_mov_b32 m0, s77
	s_nop 0
	global_load_lds_dwordx4 v[176:177], off
	v_lshl_add_u64 v[176:177], v[242:243], 0, s[12:13]
	s_mov_b32 m0, s78
	s_nop 0
	global_load_lds_dwordx4 v[176:177], off
	s_waitcnt vmcnt(8)
	s_waitcnt lgkmcnt(0)
	s_barrier
	s_setprio 1
	s_waitcnt lgkmcnt(0)
	v_mfma_f32_16x16x32_bf16 v[70:73], v[146:149], v[202:205], v[70:73]
	v_mfma_f32_16x16x32_bf16 v[66:69], v[160:163], v[202:205], v[66:69]
	v_mfma_f32_16x16x32_bf16 v[86:89], v[146:149], v[210:213], v[86:89]
	v_mfma_f32_16x16x32_bf16 v[82:85], v[160:163], v[210:213], v[82:85]
	v_mfma_f32_16x16x32_bf16 v[102:105], v[146:149], v[218:221], v[102:105]
	v_mfma_f32_16x16x32_bf16 v[98:101], v[160:163], v[218:221], v[98:101]
	v_mfma_f32_16x16x32_bf16 v[118:121], v[146:149], v[226:229], v[118:121]
	v_mfma_f32_16x16x32_bf16 v[114:117], v[160:163], v[226:229], v[114:117]
	v_mfma_f32_16x16x32_bf16 v[70:73], v[156:159], v[206:209], v[70:73]
	v_mfma_f32_16x16x32_bf16 v[66:69], v[164:167], v[206:209], v[66:69]
	v_mfma_f32_16x16x32_bf16 v[86:89], v[156:159], v[214:217], v[86:89]
	v_mfma_f32_16x16x32_bf16 v[82:85], v[164:167], v[214:217], v[82:85]
	v_mfma_f32_16x16x32_bf16 v[102:105], v[156:159], v[222:225], v[102:105]
	v_mfma_f32_16x16x32_bf16 v[98:101], v[164:167], v[222:225], v[98:101]
	v_mfma_f32_16x16x32_bf16 v[118:121], v[156:159], v[230:233], v[118:121]
	v_mfma_f32_16x16x32_bf16 v[114:117], v[164:167], v[230:233], v[114:117]
	s_setprio 0
	s_setprio 1
	v_mfma_f32_16x16x32_bf16 v[78:81], v[168:171], v[202:205], v[78:81]
	v_mfma_f32_16x16x32_bf16 v[74:77], v[182:185], v[202:205], v[74:77]
	v_mfma_f32_16x16x32_bf16 v[94:97], v[168:171], v[210:213], v[94:97]
	v_mfma_f32_16x16x32_bf16 v[90:93], v[182:185], v[210:213], v[90:93]
	v_mfma_f32_16x16x32_bf16 v[110:113], v[168:171], v[218:221], v[110:113]
	v_mfma_f32_16x16x32_bf16 v[106:109], v[182:185], v[218:221], v[106:109]
	v_mfma_f32_16x16x32_bf16 v[126:129], v[168:171], v[226:229], v[126:129]
	v_mfma_f32_16x16x32_bf16 v[122:125], v[182:185], v[226:229], v[122:125]
	v_mfma_f32_16x16x32_bf16 v[78:81], v[172:175], v[206:209], v[78:81]
	v_mfma_f32_16x16x32_bf16 v[74:77], v[198:201], v[206:209], v[74:77]
	v_mfma_f32_16x16x32_bf16 v[94:97], v[172:175], v[214:217], v[94:97]
	v_mfma_f32_16x16x32_bf16 v[90:93], v[198:201], v[214:217], v[90:93]
	v_mfma_f32_16x16x32_bf16 v[110:113], v[172:175], v[222:225], v[110:113]
	v_mfma_f32_16x16x32_bf16 v[106:109], v[198:201], v[222:225], v[106:109]
	v_mfma_f32_16x16x32_bf16 v[126:129], v[172:175], v[230:233], v[126:129]
	v_mfma_f32_16x16x32_bf16 v[122:125], v[198:201], v[230:233], v[122:125]
	s_setprio 0
	s_add_u32 s16, s16, 0x100
	s_addc_u32 s17, s17, 0
	v_lshl_add_u64 v[144:145], v[144:145], 0, s[88:89]
	v_lshl_add_u64 v[142:143], v[142:143], 0, s[88:89]
	s_cmp_ge_u32 s3, s76
	s_mov_b32 s14, s3
	s_barrier
	s_cbranch_scc0 .LBB0_538
	s_and_b64 vcc, exec, s[62:63]
	s_cbranch_vccz .LBB0_541
	s_barrier
